# hand-written bf16 epilogue for MLA in-proj GEMMs (P2/P18) with merged ssq atomics and 8-head k_rope broadcast
# speedup vs baseline: 1.1077x; 1.0154x over previous
.LBB0_307:
	ds_read_b128 v[128:131], v233
	ds_read_b128 v[136:139], v237
	ds_read_b128 v[132:135], v233 offset:4096
	ds_read_b128 v[140:143], v237 offset:4096
	ds_read_b128 v[144:147], v237 offset:8192
	ds_read_b128 v[148:151], v237 offset:12288
	s_waitcnt lgkmcnt(6)
	v_mfma_f32_32x32x16_bf16 v[112:127], v[206:209], v[216:219], v[112:127]
	v_mfma_f32_32x32x16_bf16 v[48:63], v[212:215], v[216:219], v[48:63]
	v_mfma_f32_32x32x16_bf16 v[96:111], v[206:209], v[220:223], v[96:111]
	v_mfma_f32_32x32x16_bf16 v[32:47], v[212:215], v[220:223], v[32:47]
	v_mfma_f32_32x32x16_bf16 v[80:95], v[206:209], v[224:227], v[80:95]
	v_mfma_f32_32x32x16_bf16 v[16:31], v[212:215], v[224:227], v[16:31]
	v_mfma_f32_32x32x16_bf16 v[64:79], v[206:209], v[228:231], v[64:79]
	v_mfma_f32_32x32x16_bf16 v[0:15], v[212:215], v[228:231], v[0:15]
	ds_read_b128 v[206:209], v234
	ds_read_b128 v[216:219], v238
	ds_read_b128 v[212:215], v234 offset:4096
	ds_read_b128 v[220:223], v238 offset:4096
	ds_read_b128 v[224:227], v238 offset:8192
	ds_read_b128 v[228:231], v238 offset:12288
	s_waitcnt lgkmcnt(6)
	v_mfma_f32_32x32x16_bf16 v[112:127], v[128:131], v[136:139], v[112:127]
	v_mfma_f32_32x32x16_bf16 v[48:63], v[132:135], v[136:139], v[48:63]
	v_mfma_f32_32x32x16_bf16 v[96:111], v[128:131], v[140:143], v[96:111]
	v_mfma_f32_32x32x16_bf16 v[32:47], v[132:135], v[140:143], v[32:47]
	v_mfma_f32_32x32x16_bf16 v[80:95], v[128:131], v[144:147], v[80:95]
	v_mfma_f32_32x32x16_bf16 v[16:31], v[132:135], v[144:147], v[16:31]
	v_mfma_f32_32x32x16_bf16 v[64:79], v[128:131], v[148:151], v[64:79]
	v_mfma_f32_32x32x16_bf16 v[0:15], v[132:135], v[148:151], v[0:15]
	ds_read_b128 v[128:131], v235
	ds_read_b128 v[136:139], v239
	ds_read_b128 v[132:135], v235 offset:4096
	ds_read_b128 v[140:143], v239 offset:4096
	ds_read_b128 v[144:147], v239 offset:8192
	ds_read_b128 v[148:151], v239 offset:12288
	s_waitcnt lgkmcnt(6)
	v_mfma_f32_32x32x16_bf16 v[112:127], v[206:209], v[216:219], v[112:127]
	v_mfma_f32_32x32x16_bf16 v[48:63], v[212:215], v[216:219], v[48:63]
	v_mfma_f32_32x32x16_bf16 v[96:111], v[206:209], v[220:223], v[96:111]
	v_mfma_f32_32x32x16_bf16 v[32:47], v[212:215], v[220:223], v[32:47]
	v_mfma_f32_32x32x16_bf16 v[80:95], v[206:209], v[224:227], v[80:95]
	v_mfma_f32_32x32x16_bf16 v[16:31], v[212:215], v[224:227], v[16:31]
	v_mfma_f32_32x32x16_bf16 v[64:79], v[206:209], v[228:231], v[64:79]
	v_mfma_f32_32x32x16_bf16 v[0:15], v[212:215], v[228:231], v[0:15]
	s_waitcnt vmcnt(0) lgkmcnt(0)
	s_barrier
	v_xor_b32_e32 v232, 0x10000, v232
	v_xor_b32_e32 v236, 0x10000, v236
	v_mfma_f32_32x32x16_bf16 v[112:127], v[128:131], v[136:139], v[112:127]
	v_xor_b32_e32 v233, 0x10000, v233
	v_xor_b32_e32 v237, 0x10000, v237
	v_mfma_f32_32x32x16_bf16 v[48:63], v[132:135], v[136:139], v[48:63]
	v_xor_b32_e32 v234, 0x10000, v234
	v_xor_b32_e32 v238, 0x10000, v238
	v_mfma_f32_32x32x16_bf16 v[96:111], v[128:131], v[140:143], v[96:111]
	v_xor_b32_e32 v235, 0x10000, v235
	v_xor_b32_e32 v239, 0x10000, v239
	v_mfma_f32_32x32x16_bf16 v[32:47], v[132:135], v[140:143], v[32:47]
	v_mfma_f32_32x32x16_bf16 v[80:95], v[128:131], v[144:147], v[80:95]
	v_mfma_f32_32x32x16_bf16 v[16:31], v[132:135], v[144:147], v[16:31]
	v_mfma_f32_32x32x16_bf16 v[64:79], v[128:131], v[148:151], v[64:79]
	v_mfma_f32_32x32x16_bf16 v[0:15], v[132:135], v[148:151], v[0:15]
	v_mbcnt_hi_u32_b32 v230, -1, v210
	v_and_b32_e32 v231, 31, v230
	v_lshrrev_b32_e32 v232, 5, v230
	v_lshlrev_b32_e32 v224, 3, v231
	v_lshlrev_b32_e32 v227, 2, v232
	s_lshr_b32 s90, s70, 6
	s_mul_i32 s91, s90, 0x1200
	s_add_u32 s91, s91, 0x12000
	v_mul_u32_u24_e32 v233, 0x240, v232
	v_lshl_add_u32 v233, v231, 1, v233
	v_add_u32_e32 v225, s91, v233
	v_lshrrev_b32_e32 v228, 3, v230
	v_and_b32_e32 v234, 7, v230
	v_lshlrev_b32_e32 v229, 4, v234
	v_mul_u32_u24_e32 v233, 0x90, v228
	v_add3_u32 v226, v233, v229, s91
	s_mul_i32 s92, s5, 6
	s_sub_u32 s93, s4, s92
	s_lshl_b32 s93, s93, 8
	s_lshl_b32 s92, s5, 8
	s_lshr_b32 s94, s90, 1
	s_lshl_b32 s94, s94, 6
	s_add_u32 s92, s92, s94
	s_and_b32 s94, s90, 1
	s_lshl_b32 s94, s94, 7
	s_add_u32 s93, s93, s94
.Lep0_00:
	s_add_u32 s94, s92, 0
	s_add_u32 s95, s93, 0
	s_lshr_b32 s90, s95, 6
	s_cmp_lt_u32 s90, 4
	s_cbranch_scc1 .Lep0_00_t0
	s_cmp_lt_u32 s90, 6
	s_cbranch_scc1 .Lep0_00_t4
	s_cmp_lt_u32 s90, 7
	s_cbranch_scc1 .Lep0_00_t6
	s_cmp_lt_u32 s90, 23
	s_cbranch_scc1 .Lep0_00_t7
	s_branch .Lep0_00_end
.Lep0_00_t0:
	s_load_dwordx2 s[96:97], s[0:1], 0x168
	s_mov_b32 s89, 512
	s_sub_u32 s91, s95, 0
	s_lshl_b32 s91, s91, 1
	s_load_dwordx2 s[98:99], s[0:1], 0x210
	s_branch .Lep0_00_mP
.Lep0_00_t4:
	s_load_dwordx2 s[96:97], s[0:1], 0x170
	s_mov_b32 s89, 256
	s_sub_u32 s91, s95, 256
	s_lshl_b32 s91, s91, 1
	s_load_dwordx2 s[98:99], s[0:1], 0x218
	s_branch .Lep0_00_mP
.Lep0_00_t6:
	s_load_dwordx2 s[96:97], s[0:1], 0x180
	s_mov_b32 s89, 0
	s_sub_u32 s91, s95, 384
	s_lshl_b32 s91, s91, 1
	s_mov_b32 s88, 1.0
	s_branch .Lep0_00_mR
.Lep0_00_t7:
	s_load_dwordx2 s[96:97], s[0:1], 0x160
	s_mov_b32 s89, 2048
	s_sub_u32 s91, s95, 448
	s_lshl_b32 s91, s91, 1
	s_branch .Lep0_00_mS

.Lep0_00_mR:
	s_load_dwordx2 s[98:99], s[0:1], 0x148
	v_add_u32_e32 v230, s94, v227
	v_lshlrev_b32_e32 v230, 8, v230
	v_add_u32_e32 v236, v230, v224
	v_mov_b32_e32 v237, 0
	s_waitcnt lgkmcnt(0)
	v_lshl_add_u64 v[236:237], s[98:99], 0, v[236:237]
	global_load_dwordx2 v[128:129], v[236:237], off
	global_load_dwordx2 v[130:131], v[236:237], off offset:256
	global_load_dwordx2 v[132:133], v[236:237], off offset:512
	global_load_dwordx2 v[134:135], v[236:237], off offset:768
	global_load_dwordx2 v[136:137], v[236:237], off offset:2048
	global_load_dwordx2 v[138:139], v[236:237], off offset:2304
	global_load_dwordx2 v[140:141], v[236:237], off offset:2560
	global_load_dwordx2 v[142:143], v[236:237], off offset:2816
	v_add_co_u32_e32 v238, vcc, 0x1000, v236
	s_nop 1
	v_addc_co_u32_e32 v239, vcc, 0, v237, vcc
	global_load_dwordx2 v[144:145], v[238:239], off
	global_load_dwordx2 v[146:147], v[238:239], off offset:256
	global_load_dwordx2 v[148:149], v[238:239], off offset:512
	global_load_dwordx2 v[150:151], v[238:239], off offset:768
	global_load_dwordx2 v[152:153], v[238:239], off offset:2048
	global_load_dwordx2 v[154:155], v[238:239], off offset:2304
	global_load_dwordx2 v[156:157], v[238:239], off offset:2560
	global_load_dwordx2 v[158:159], v[238:239], off offset:2816
	s_waitcnt vmcnt(15)
	v_mul_f32_e32 v230, v96, v129
	v_mul_f32_e32 v231, v112, v129
	v_fma_f32 v230, v112, v128, -v230
	v_fma_f32 v231, v96, v128, v231
	v_mul_f32_e32 v230, s88, v230
	v_mul_f32_e32 v231, s88, v231
	v_cvt_pk_bf16_f32 v230, v230, v231
	ds_write_b16 v225, v230
	ds_write_b16_d16_hi v225, v230 offset:64
	s_waitcnt vmcnt(14)
	v_mul_f32_e32 v230, v97, v131
	v_mul_f32_e32 v231, v113, v131
	v_fma_f32 v230, v113, v130, -v230
	v_fma_f32 v231, v97, v130, v231
	v_mul_f32_e32 v230, s88, v230
	v_mul_f32_e32 v231, s88, v231
	v_cvt_pk_bf16_f32 v230, v230, v231
	ds_write_b16 v225, v230 offset:144
	ds_write_b16_d16_hi v225, v230 offset:208
	s_waitcnt vmcnt(13)
	v_mul_f32_e32 v230, v98, v133
	v_mul_f32_e32 v231, v114, v133
	v_fma_f32 v230, v114, v132, -v230
	v_fma_f32 v231, v98, v132, v231
	v_mul_f32_e32 v230, s88, v230
	v_mul_f32_e32 v231, s88, v231
	v_cvt_pk_bf16_f32 v230, v230, v231
	ds_write_b16 v225, v230 offset:288
	ds_write_b16_d16_hi v225, v230 offset:352
	s_waitcnt vmcnt(12)
	v_mul_f32_e32 v230, v99, v135
	v_mul_f32_e32 v231, v115, v135
	v_fma_f32 v230, v115, v134, -v230
	v_fma_f32 v231, v99, v134, v231
	v_mul_f32_e32 v230, s88, v230
	v_mul_f32_e32 v231, s88, v231
	v_cvt_pk_bf16_f32 v230, v230, v231
	ds_write_b16 v225, v230 offset:432
	ds_write_b16_d16_hi v225, v230 offset:496
	s_waitcnt vmcnt(11)
	v_mul_f32_e32 v230, v100, v137
	v_mul_f32_e32 v231, v116, v137
	v_fma_f32 v230, v116, v136, -v230
	v_fma_f32 v231, v100, v136, v231
	v_mul_f32_e32 v230, s88, v230
	v_mul_f32_e32 v231, s88, v231
	v_cvt_pk_bf16_f32 v230, v230, v231
	ds_write_b16 v225, v230 offset:1152
	ds_write_b16_d16_hi v225, v230 offset:1216
	s_waitcnt vmcnt(10)
	v_mul_f32_e32 v230, v101, v139
	v_mul_f32_e32 v231, v117, v139
	v_fma_f32 v230, v117, v138, -v230
	v_fma_f32 v231, v101, v138, v231
	v_mul_f32_e32 v230, s88, v230
	v_mul_f32_e32 v231, s88, v231
	v_cvt_pk_bf16_f32 v230, v230, v231
	ds_write_b16 v225, v230 offset:1296
	ds_write_b16_d16_hi v225, v230 offset:1360
	s_waitcnt vmcnt(9)
	v_mul_f32_e32 v230, v102, v141
	v_mul_f32_e32 v231, v118, v141
	v_fma_f32 v230, v118, v140, -v230
	v_fma_f32 v231, v102, v140, v231
	v_mul_f32_e32 v230, s88, v230
	v_mul_f32_e32 v231, s88, v231
	v_cvt_pk_bf16_f32 v230, v230, v231
	ds_write_b16 v225, v230 offset:1440
	ds_write_b16_d16_hi v225, v230 offset:1504
	s_waitcnt vmcnt(8)
	v_mul_f32_e32 v230, v103, v143
	v_mul_f32_e32 v231, v119, v143
	v_fma_f32 v230, v119, v142, -v230
	v_fma_f32 v231, v103, v142, v231
	v_mul_f32_e32 v230, s88, v230
	v_mul_f32_e32 v231, s88, v231
	v_cvt_pk_bf16_f32 v230, v230, v231
	ds_write_b16 v225, v230 offset:1584
	ds_write_b16_d16_hi v225, v230 offset:1648
	s_waitcnt vmcnt(7)
	v_mul_f32_e32 v230, v104, v145
	v_mul_f32_e32 v231, v120, v145
	v_fma_f32 v230, v120, v144, -v230
	v_fma_f32 v231, v104, v144, v231
	v_mul_f32_e32 v230, s88, v230
	v_mul_f32_e32 v231, s88, v231
	v_cvt_pk_bf16_f32 v230, v230, v231
	ds_write_b16 v225, v230 offset:2304
	ds_write_b16_d16_hi v225, v230 offset:2368
	s_waitcnt vmcnt(6)
	v_mul_f32_e32 v230, v105, v147
	v_mul_f32_e32 v231, v121, v147
	v_fma_f32 v230, v121, v146, -v230
	v_fma_f32 v231, v105, v146, v231
	v_mul_f32_e32 v230, s88, v230
	v_mul_f32_e32 v231, s88, v231
	v_cvt_pk_bf16_f32 v230, v230, v231
	ds_write_b16 v225, v230 offset:2448
	ds_write_b16_d16_hi v225, v230 offset:2512
	s_waitcnt vmcnt(5)
	v_mul_f32_e32 v230, v106, v149
	v_mul_f32_e32 v231, v122, v149
	v_fma_f32 v230, v122, v148, -v230
	v_fma_f32 v231, v106, v148, v231
	v_mul_f32_e32 v230, s88, v230
	v_mul_f32_e32 v231, s88, v231
	v_cvt_pk_bf16_f32 v230, v230, v231
	ds_write_b16 v225, v230 offset:2592
	ds_write_b16_d16_hi v225, v230 offset:2656
	s_waitcnt vmcnt(4)
	v_mul_f32_e32 v230, v107, v151
	v_mul_f32_e32 v231, v123, v151
	v_fma_f32 v230, v123, v150, -v230
	v_fma_f32 v231, v107, v150, v231
	v_mul_f32_e32 v230, s88, v230
	v_mul_f32_e32 v231, s88, v231
	v_cvt_pk_bf16_f32 v230, v230, v231
	ds_write_b16 v225, v230 offset:2736
	ds_write_b16_d16_hi v225, v230 offset:2800
	s_waitcnt vmcnt(3)
	v_mul_f32_e32 v230, v108, v153
	v_mul_f32_e32 v231, v124, v153
	v_fma_f32 v230, v124, v152, -v230
	v_fma_f32 v231, v108, v152, v231
	v_mul_f32_e32 v230, s88, v230
	v_mul_f32_e32 v231, s88, v231
	v_cvt_pk_bf16_f32 v230, v230, v231
	ds_write_b16 v225, v230 offset:3456
	ds_write_b16_d16_hi v225, v230 offset:3520
	s_waitcnt vmcnt(2)
	v_mul_f32_e32 v230, v109, v155
	v_mul_f32_e32 v231, v125, v155
	v_fma_f32 v230, v125, v154, -v230
	v_fma_f32 v231, v109, v154, v231
	v_mul_f32_e32 v230, s88, v230
	v_mul_f32_e32 v231, s88, v231
	v_cvt_pk_bf16_f32 v230, v230, v231
	ds_write_b16 v225, v230 offset:3600
	ds_write_b16_d16_hi v225, v230 offset:3664
	s_waitcnt vmcnt(1)
	v_mul_f32_e32 v230, v110, v157
	v_mul_f32_e32 v231, v126, v157
	v_fma_f32 v230, v126, v156, -v230
	v_fma_f32 v231, v110, v156, v231
	v_mul_f32_e32 v230, s88, v230
	v_mul_f32_e32 v231, s88, v231
	v_cvt_pk_bf16_f32 v230, v230, v231
	ds_write_b16 v225, v230 offset:3744
	ds_write_b16_d16_hi v225, v230 offset:3808
	s_waitcnt vmcnt(0)
	v_mul_f32_e32 v230, v111, v159
	v_mul_f32_e32 v231, v127, v159
	v_fma_f32 v230, v127, v158, -v230
	v_fma_f32 v231, v111, v158, v231
	v_mul_f32_e32 v230, s88, v230
	v_mul_f32_e32 v231, s88, v231
	v_cvt_pk_bf16_f32 v230, v230, v231
	ds_write_b16 v225, v230 offset:3888
	ds_write_b16_d16_hi v225, v230 offset:3952
	s_branch .Lep0_00_stb

.Lep0_00_stq:
	v_add_u32_e32 v234, s94, v228
	s_waitcnt lgkmcnt(0)
	ds_read_b128 v[206:209], v226
	ds_read_b128 v[212:215], v226 offset:1152
	ds_read_b128 v[216:219], v226 offset:2304
	ds_read_b128 v[220:223], v226 offset:3456
	v_add_u32_e32 v230, 0, v234
	v_mul_lo_u32 v230, v230, s89
	v_add3_u32 v230, v230, v229, s91
	v_add_u32_e32 v231, 8, v234
	v_mul_lo_u32 v231, v231, s89
	v_add3_u32 v231, v231, v229, s91
	v_add_u32_e32 v232, 16, v234
	v_mul_lo_u32 v232, v232, s89
	v_add3_u32 v232, v232, v229, s91
	v_add_u32_e32 v233, 24, v234
	v_mul_lo_u32 v233, v233, s89
	v_add3_u32 v233, v233, v229, s91
	s_waitcnt lgkmcnt(3)
	global_store_dwordx4 v230, v[206:209], s[96:97]
	s_waitcnt lgkmcnt(2)
	global_store_dwordx4 v231, v[212:215], s[96:97]
	s_waitcnt lgkmcnt(1)
	global_store_dwordx4 v232, v[216:219], s[96:97]
	s_waitcnt lgkmcnt(0)
	global_store_dwordx4 v233, v[220:223], s[96:97]
	v_lshlrev_b32_e32 v132, 16, v206
	v_and_b32_e32 v133, 0xffff0000, v206
	v_mul_f32_e32 v128, v132, v132
	v_fma_f32 v128, v133, v133, v128
	v_lshlrev_b32_e32 v132, 16, v207
	v_and_b32_e32 v133, 0xffff0000, v207
	v_fma_f32 v128, v132, v132, v128
	v_fma_f32 v128, v133, v133, v128
	v_lshlrev_b32_e32 v132, 16, v208
	v_and_b32_e32 v133, 0xffff0000, v208
	v_fma_f32 v128, v132, v132, v128
	v_fma_f32 v128, v133, v133, v128
	v_lshlrev_b32_e32 v132, 16, v209
	v_and_b32_e32 v133, 0xffff0000, v209
	v_fma_f32 v128, v132, v132, v128
	v_fma_f32 v128, v133, v133, v128
	v_lshlrev_b32_e32 v132, 16, v212
	v_and_b32_e32 v133, 0xffff0000, v212
	v_mul_f32_e32 v129, v132, v132
	v_fma_f32 v129, v133, v133, v129
	v_lshlrev_b32_e32 v132, 16, v213
	v_and_b32_e32 v133, 0xffff0000, v213
	v_fma_f32 v129, v132, v132, v129
	v_fma_f32 v129, v133, v133, v129
	v_lshlrev_b32_e32 v132, 16, v214
	v_and_b32_e32 v133, 0xffff0000, v214
	v_fma_f32 v129, v132, v132, v129
	v_fma_f32 v129, v133, v133, v129
	v_lshlrev_b32_e32 v132, 16, v215
	v_and_b32_e32 v133, 0xffff0000, v215
	v_fma_f32 v129, v132, v132, v129
	v_fma_f32 v129, v133, v133, v129
	v_lshlrev_b32_e32 v132, 16, v216
	v_and_b32_e32 v133, 0xffff0000, v216
	v_mul_f32_e32 v130, v132, v132
	v_fma_f32 v130, v133, v133, v130
	v_lshlrev_b32_e32 v132, 16, v217
	v_and_b32_e32 v133, 0xffff0000, v217
	v_fma_f32 v130, v132, v132, v130
	v_fma_f32 v130, v133, v133, v130
	v_lshlrev_b32_e32 v132, 16, v218
	v_and_b32_e32 v133, 0xffff0000, v218
	v_fma_f32 v130, v132, v132, v130
	v_fma_f32 v130, v133, v133, v130
	v_lshlrev_b32_e32 v132, 16, v219
	v_and_b32_e32 v133, 0xffff0000, v219
	v_fma_f32 v130, v132, v132, v130
	v_fma_f32 v130, v133, v133, v130
	v_lshlrev_b32_e32 v132, 16, v220
	v_and_b32_e32 v133, 0xffff0000, v220
	v_mul_f32_e32 v131, v132, v132
	v_fma_f32 v131, v133, v133, v131
	v_lshlrev_b32_e32 v132, 16, v221
	v_and_b32_e32 v133, 0xffff0000, v221
	v_fma_f32 v131, v132, v132, v131
	v_fma_f32 v131, v133, v133, v131
	v_lshlrev_b32_e32 v132, 16, v222
	v_and_b32_e32 v133, 0xffff0000, v222
	v_fma_f32 v131, v132, v132, v131
	v_fma_f32 v131, v133, v133, v131
	v_lshlrev_b32_e32 v132, 16, v223
	v_and_b32_e32 v133, 0xffff0000, v223
	v_fma_f32 v131, v132, v132, v131
	v_fma_f32 v131, v133, v133, v131
	s_nop 1
	v_add_f32_dpp v136, v128, v128 quad_perm:[1,0,3,2] row_mask:0xf bank_mask:0xf
	v_add_f32_dpp v137, v129, v129 quad_perm:[1,0,3,2] row_mask:0xf bank_mask:0xf
	v_add_f32_dpp v138, v130, v130 quad_perm:[1,0,3,2] row_mask:0xf bank_mask:0xf
	v_add_f32_dpp v139, v131, v131 quad_perm:[1,0,3,2] row_mask:0xf bank_mask:0xf
	v_add_f32_dpp v128, v136, v136 quad_perm:[2,3,0,1] row_mask:0xf bank_mask:0xf
	v_add_f32_dpp v129, v137, v137 quad_perm:[2,3,0,1] row_mask:0xf bank_mask:0xf
	v_add_f32_dpp v130, v138, v138 quad_perm:[2,3,0,1] row_mask:0xf bank_mask:0xf
	v_add_f32_dpp v131, v139, v139 quad_perm:[2,3,0,1] row_mask:0xf bank_mask:0xf
	v_add_f32_dpp v236, v128, v128 row_half_mirror row_mask:0xf bank_mask:0xf
	v_add_f32_dpp v237, v129, v129 row_half_mirror row_mask:0xf bank_mask:0xf
	v_add_f32_dpp v238, v130, v130 row_half_mirror row_mask:0xf bank_mask:0xf
	v_add_f32_dpp v239, v131, v131 row_half_mirror row_mask:0xf bank_mask:0xf
	s_branch .Lep0_00_end
.Lep0_00_stb:
	v_add_u32_e32 v234, s94, v228
	s_waitcnt lgkmcnt(0)
	ds_read_b128 v[206:209], v226
	ds_read_b128 v[212:215], v226 offset:1152
	ds_read_b128 v[216:219], v226 offset:2304
	ds_read_b128 v[220:223], v226 offset:3456
	s_mov_b32 s88, 0xc00000
	s_mov_b32 s89, 0x180
	v_add_u32_e32 v230, 0, v234
	v_lshrrev_b32_e32 v128, 12, v230
	v_and_b32_e32 v230, 0xfff, v230
	v_mul_lo_u32 v128, v128, s88
	v_mul_lo_u32 v230, v230, s89
	v_add3_u32 v230, v230, v128, v229
	v_add_u32_e32 v231, 8, v234
	v_lshrrev_b32_e32 v129, 12, v231
	v_and_b32_e32 v231, 0xfff, v231
	v_mul_lo_u32 v129, v129, s88
	v_mul_lo_u32 v231, v231, s89
	v_add3_u32 v231, v231, v129, v229
	v_add_u32_e32 v232, 16, v234
	v_lshrrev_b32_e32 v130, 12, v232
	v_and_b32_e32 v232, 0xfff, v232
	v_mul_lo_u32 v130, v130, s88
	v_mul_lo_u32 v232, v232, s89
	v_add3_u32 v232, v232, v130, v229
	v_add_u32_e32 v233, 24, v234
	v_lshrrev_b32_e32 v131, 12, v233
	v_and_b32_e32 v233, 0xfff, v233
	v_mul_lo_u32 v131, v131, s88
	v_mul_lo_u32 v233, v233, s89
	v_add3_u32 v233, v233, v131, v229
	s_waitcnt lgkmcnt(3)
	global_store_dwordx4 v230, v[206:209], s[96:97] offset:256
	v_add_u32_e32 v230, 0x180000, v230
	s_waitcnt lgkmcnt(2)
	global_store_dwordx4 v231, v[212:215], s[96:97] offset:256
	v_add_u32_e32 v231, 0x180000, v231
	s_waitcnt lgkmcnt(1)
	global_store_dwordx4 v232, v[216:219], s[96:97] offset:256
	v_add_u32_e32 v232, 0x180000, v232
	s_waitcnt lgkmcnt(0)
	global_store_dwordx4 v233, v[220:223], s[96:97] offset:256
	v_add_u32_e32 v233, 0x180000, v233
	global_store_dwordx4 v230, v[206:209], s[96:97] offset:256
	v_add_u32_e32 v230, 0x180000, v230
	global_store_dwordx4 v231, v[212:215], s[96:97] offset:256
	v_add_u32_e32 v231, 0x180000, v231
	global_store_dwordx4 v232, v[216:219], s[96:97] offset:256
	v_add_u32_e32 v232, 0x180000, v232
	global_store_dwordx4 v233, v[220:223], s[96:97] offset:256
	v_add_u32_e32 v233, 0x180000, v233
	global_store_dwordx4 v230, v[206:209], s[96:97] offset:256
	v_add_u32_e32 v230, 0x180000, v230
	global_store_dwordx4 v231, v[212:215], s[96:97] offset:256
	v_add_u32_e32 v231, 0x180000, v231
	global_store_dwordx4 v232, v[216:219], s[96:97] offset:256
	v_add_u32_e32 v232, 0x180000, v232
	global_store_dwordx4 v233, v[220:223], s[96:97] offset:256
	v_add_u32_e32 v233, 0x180000, v233
	global_store_dwordx4 v230, v[206:209], s[96:97] offset:256
	v_add_u32_e32 v230, 0x180000, v230
	global_store_dwordx4 v231, v[212:215], s[96:97] offset:256
	v_add_u32_e32 v231, 0x180000, v231
	global_store_dwordx4 v232, v[216:219], s[96:97] offset:256
	v_add_u32_e32 v232, 0x180000, v232
	global_store_dwordx4 v233, v[220:223], s[96:97] offset:256
	v_add_u32_e32 v233, 0x180000, v233
	global_store_dwordx4 v230, v[206:209], s[96:97] offset:256
	v_add_u32_e32 v230, 0x180000, v230
	global_store_dwordx4 v231, v[212:215], s[96:97] offset:256
	v_add_u32_e32 v231, 0x180000, v231
	global_store_dwordx4 v232, v[216:219], s[96:97] offset:256
	v_add_u32_e32 v232, 0x180000, v232
	global_store_dwordx4 v233, v[220:223], s[96:97] offset:256
	v_add_u32_e32 v233, 0x180000, v233
	global_store_dwordx4 v230, v[206:209], s[96:97] offset:256
	v_add_u32_e32 v230, 0x180000, v230
	global_store_dwordx4 v231, v[212:215], s[96:97] offset:256
	v_add_u32_e32 v231, 0x180000, v231
	global_store_dwordx4 v232, v[216:219], s[96:97] offset:256
	v_add_u32_e32 v232, 0x180000, v232
	global_store_dwordx4 v233, v[220:223], s[96:97] offset:256
	v_add_u32_e32 v233, 0x180000, v233
	global_store_dwordx4 v230, v[206:209], s[96:97] offset:256
	v_add_u32_e32 v230, 0x180000, v230
	global_store_dwordx4 v231, v[212:215], s[96:97] offset:256
	v_add_u32_e32 v231, 0x180000, v231
	global_store_dwordx4 v232, v[216:219], s[96:97] offset:256
	v_add_u32_e32 v232, 0x180000, v232
	global_store_dwordx4 v233, v[220:223], s[96:97] offset:256
	v_add_u32_e32 v233, 0x180000, v233
	global_store_dwordx4 v230, v[206:209], s[96:97] offset:256
	global_store_dwordx4 v231, v[212:215], s[96:97] offset:256
	global_store_dwordx4 v232, v[216:219], s[96:97] offset:256
	global_store_dwordx4 v233, v[220:223], s[96:97] offset:256
	s_branch .Lep0_00_end
.Lep0_00_st:
	v_add_u32_e32 v234, s94, v228
	s_waitcnt lgkmcnt(0)
	ds_read_b128 v[206:209], v226
	ds_read_b128 v[212:215], v226 offset:1152
	ds_read_b128 v[216:219], v226 offset:2304
	ds_read_b128 v[220:223], v226 offset:3456
	v_add_u32_e32 v230, 0, v234
	v_mul_lo_u32 v230, v230, s89
	v_add3_u32 v230, v230, v229, s91
	v_add_u32_e32 v231, 8, v234
	v_mul_lo_u32 v231, v231, s89
	v_add3_u32 v231, v231, v229, s91
	v_add_u32_e32 v232, 16, v234
	v_mul_lo_u32 v232, v232, s89
	v_add3_u32 v232, v232, v229, s91
	v_add_u32_e32 v233, 24, v234
	v_mul_lo_u32 v233, v233, s89
	v_add3_u32 v233, v233, v229, s91
	s_waitcnt lgkmcnt(3)
	global_store_dwordx4 v230, v[206:209], s[96:97]
	s_waitcnt lgkmcnt(2)
	global_store_dwordx4 v231, v[212:215], s[96:97]
	s_waitcnt lgkmcnt(1)
	global_store_dwordx4 v232, v[216:219], s[96:97]
	s_waitcnt lgkmcnt(0)
	global_store_dwordx4 v233, v[220:223], s[96:97]
.Lep0_00_end:
.Lep0_01:
	s_add_u32 s94, s92, 0
	s_add_u32 s95, s93, 64
	s_lshr_b32 s90, s95, 6
	s_cmp_lt_u32 s90, 4
	s_cbranch_scc1 .Lep0_01_t0
	s_cmp_lt_u32 s90, 6
	s_cbranch_scc1 .Lep0_01_t4
	s_cmp_lt_u32 s90, 7
	s_cbranch_scc1 .Lep0_01_t6
	s_cmp_lt_u32 s90, 23
	s_cbranch_scc1 .Lep0_01_t7
	s_branch .Lep0_01_end

.Lep0_01_mR:
	s_load_dwordx2 s[98:99], s[0:1], 0x148
	v_add_u32_e32 v230, s94, v227
	v_lshlrev_b32_e32 v230, 8, v230
	v_add_u32_e32 v236, v230, v224
	v_mov_b32_e32 v237, 0
	s_waitcnt lgkmcnt(0)
	v_lshl_add_u64 v[236:237], s[98:99], 0, v[236:237]
	global_load_dwordx2 v[128:129], v[236:237], off
	global_load_dwordx2 v[130:131], v[236:237], off offset:256
	global_load_dwordx2 v[132:133], v[236:237], off offset:512
	global_load_dwordx2 v[134:135], v[236:237], off offset:768
	global_load_dwordx2 v[136:137], v[236:237], off offset:2048
	global_load_dwordx2 v[138:139], v[236:237], off offset:2304
	global_load_dwordx2 v[140:141], v[236:237], off offset:2560
	global_load_dwordx2 v[142:143], v[236:237], off offset:2816
	v_add_co_u32_e32 v238, vcc, 0x1000, v236
	s_nop 1
	v_addc_co_u32_e32 v239, vcc, 0, v237, vcc
	global_load_dwordx2 v[144:145], v[238:239], off
	global_load_dwordx2 v[146:147], v[238:239], off offset:256
	global_load_dwordx2 v[148:149], v[238:239], off offset:512
	global_load_dwordx2 v[150:151], v[238:239], off offset:768
	global_load_dwordx2 v[152:153], v[238:239], off offset:2048
	global_load_dwordx2 v[154:155], v[238:239], off offset:2304
	global_load_dwordx2 v[156:157], v[238:239], off offset:2560
	global_load_dwordx2 v[158:159], v[238:239], off offset:2816
	s_waitcnt vmcnt(15)
	v_mul_f32_e32 v230, v64, v129
	v_mul_f32_e32 v231, v80, v129
	v_fma_f32 v230, v80, v128, -v230
	v_fma_f32 v231, v64, v128, v231
	v_mul_f32_e32 v230, s88, v230
	v_mul_f32_e32 v231, s88, v231
	v_cvt_pk_bf16_f32 v230, v230, v231
	ds_write_b16 v225, v230
	ds_write_b16_d16_hi v225, v230 offset:64
	s_waitcnt vmcnt(14)
	v_mul_f32_e32 v230, v65, v131
	v_mul_f32_e32 v231, v81, v131
	v_fma_f32 v230, v81, v130, -v230
	v_fma_f32 v231, v65, v130, v231
	v_mul_f32_e32 v230, s88, v230
	v_mul_f32_e32 v231, s88, v231
	v_cvt_pk_bf16_f32 v230, v230, v231
	ds_write_b16 v225, v230 offset:144
	ds_write_b16_d16_hi v225, v230 offset:208
	s_waitcnt vmcnt(13)
	v_mul_f32_e32 v230, v66, v133
	v_mul_f32_e32 v231, v82, v133
	v_fma_f32 v230, v82, v132, -v230
	v_fma_f32 v231, v66, v132, v231
	v_mul_f32_e32 v230, s88, v230
	v_mul_f32_e32 v231, s88, v231
	v_cvt_pk_bf16_f32 v230, v230, v231
	ds_write_b16 v225, v230 offset:288
	ds_write_b16_d16_hi v225, v230 offset:352
	s_waitcnt vmcnt(12)
	v_mul_f32_e32 v230, v67, v135
	v_mul_f32_e32 v231, v83, v135
	v_fma_f32 v230, v83, v134, -v230
	v_fma_f32 v231, v67, v134, v231
	v_mul_f32_e32 v230, s88, v230
	v_mul_f32_e32 v231, s88, v231
	v_cvt_pk_bf16_f32 v230, v230, v231
	ds_write_b16 v225, v230 offset:432
	ds_write_b16_d16_hi v225, v230 offset:496
	s_waitcnt vmcnt(11)
	v_mul_f32_e32 v230, v68, v137
	v_mul_f32_e32 v231, v84, v137
	v_fma_f32 v230, v84, v136, -v230
	v_fma_f32 v231, v68, v136, v231
	v_mul_f32_e32 v230, s88, v230
	v_mul_f32_e32 v231, s88, v231
	v_cvt_pk_bf16_f32 v230, v230, v231
	ds_write_b16 v225, v230 offset:1152
	ds_write_b16_d16_hi v225, v230 offset:1216
	s_waitcnt vmcnt(10)
	v_mul_f32_e32 v230, v69, v139
	v_mul_f32_e32 v231, v85, v139
	v_fma_f32 v230, v85, v138, -v230
	v_fma_f32 v231, v69, v138, v231
	v_mul_f32_e32 v230, s88, v230
	v_mul_f32_e32 v231, s88, v231
	v_cvt_pk_bf16_f32 v230, v230, v231
	ds_write_b16 v225, v230 offset:1296
	ds_write_b16_d16_hi v225, v230 offset:1360
	s_waitcnt vmcnt(9)
	v_mul_f32_e32 v230, v70, v141
	v_mul_f32_e32 v231, v86, v141
	v_fma_f32 v230, v86, v140, -v230
	v_fma_f32 v231, v70, v140, v231
	v_mul_f32_e32 v230, s88, v230
	v_mul_f32_e32 v231, s88, v231
	v_cvt_pk_bf16_f32 v230, v230, v231
	ds_write_b16 v225, v230 offset:1440
	ds_write_b16_d16_hi v225, v230 offset:1504
	s_waitcnt vmcnt(8)
	v_mul_f32_e32 v230, v71, v143
	v_mul_f32_e32 v231, v87, v143
	v_fma_f32 v230, v87, v142, -v230
	v_fma_f32 v231, v71, v142, v231
	v_mul_f32_e32 v230, s88, v230
	v_mul_f32_e32 v231, s88, v231
	v_cvt_pk_bf16_f32 v230, v230, v231
	ds_write_b16 v225, v230 offset:1584
	ds_write_b16_d16_hi v225, v230 offset:1648
	s_waitcnt vmcnt(7)
	v_mul_f32_e32 v230, v72, v145
	v_mul_f32_e32 v231, v88, v145
	v_fma_f32 v230, v88, v144, -v230
	v_fma_f32 v231, v72, v144, v231
	v_mul_f32_e32 v230, s88, v230
	v_mul_f32_e32 v231, s88, v231
	v_cvt_pk_bf16_f32 v230, v230, v231
	ds_write_b16 v225, v230 offset:2304
	ds_write_b16_d16_hi v225, v230 offset:2368
	s_waitcnt vmcnt(6)
	v_mul_f32_e32 v230, v73, v147
	v_mul_f32_e32 v231, v89, v147
	v_fma_f32 v230, v89, v146, -v230
	v_fma_f32 v231, v73, v146, v231
	v_mul_f32_e32 v230, s88, v230
	v_mul_f32_e32 v231, s88, v231
	v_cvt_pk_bf16_f32 v230, v230, v231
	ds_write_b16 v225, v230 offset:2448
	ds_write_b16_d16_hi v225, v230 offset:2512
	s_waitcnt vmcnt(5)
	v_mul_f32_e32 v230, v74, v149
	v_mul_f32_e32 v231, v90, v149
	v_fma_f32 v230, v90, v148, -v230
	v_fma_f32 v231, v74, v148, v231
	v_mul_f32_e32 v230, s88, v230
	v_mul_f32_e32 v231, s88, v231
	v_cvt_pk_bf16_f32 v230, v230, v231
	ds_write_b16 v225, v230 offset:2592
	ds_write_b16_d16_hi v225, v230 offset:2656
	s_waitcnt vmcnt(4)
	v_mul_f32_e32 v230, v75, v151
	v_mul_f32_e32 v231, v91, v151
	v_fma_f32 v230, v91, v150, -v230
	v_fma_f32 v231, v75, v150, v231
	v_mul_f32_e32 v230, s88, v230
	v_mul_f32_e32 v231, s88, v231
	v_cvt_pk_bf16_f32 v230, v230, v231
	ds_write_b16 v225, v230 offset:2736
	ds_write_b16_d16_hi v225, v230 offset:2800
	s_waitcnt vmcnt(3)
	v_mul_f32_e32 v230, v76, v153
	v_mul_f32_e32 v231, v92, v153
	v_fma_f32 v230, v92, v152, -v230
	v_fma_f32 v231, v76, v152, v231
	v_mul_f32_e32 v230, s88, v230
	v_mul_f32_e32 v231, s88, v231
	v_cvt_pk_bf16_f32 v230, v230, v231
	ds_write_b16 v225, v230 offset:3456
	ds_write_b16_d16_hi v225, v230 offset:3520
	s_waitcnt vmcnt(2)
	v_mul_f32_e32 v230, v77, v155
	v_mul_f32_e32 v231, v93, v155
	v_fma_f32 v230, v93, v154, -v230
	v_fma_f32 v231, v77, v154, v231
	v_mul_f32_e32 v230, s88, v230
	v_mul_f32_e32 v231, s88, v231
	v_cvt_pk_bf16_f32 v230, v230, v231
	ds_write_b16 v225, v230 offset:3600
	ds_write_b16_d16_hi v225, v230 offset:3664
	s_waitcnt vmcnt(1)
	v_mul_f32_e32 v230, v78, v157
	v_mul_f32_e32 v231, v94, v157
	v_fma_f32 v230, v94, v156, -v230
	v_fma_f32 v231, v78, v156, v231
	v_mul_f32_e32 v230, s88, v230
	v_mul_f32_e32 v231, s88, v231
	v_cvt_pk_bf16_f32 v230, v230, v231
	ds_write_b16 v225, v230 offset:3744
	ds_write_b16_d16_hi v225, v230 offset:3808
	s_waitcnt vmcnt(0)
	v_mul_f32_e32 v230, v79, v159
	v_mul_f32_e32 v231, v95, v159
	v_fma_f32 v230, v95, v158, -v230
	v_fma_f32 v231, v79, v158, v231
	v_mul_f32_e32 v230, s88, v230
	v_mul_f32_e32 v231, s88, v231
	v_cvt_pk_bf16_f32 v230, v230, v231
	ds_write_b16 v225, v230 offset:3888
	ds_write_b16_d16_hi v225, v230 offset:3952
	s_branch .Lep0_01_stb

.Lep0_01_stq:
	v_add_u32_e32 v234, s94, v228
	s_waitcnt lgkmcnt(0)
	ds_read_b128 v[206:209], v226
	ds_read_b128 v[212:215], v226 offset:1152
	ds_read_b128 v[216:219], v226 offset:2304
	ds_read_b128 v[220:223], v226 offset:3456
	v_add_u32_e32 v230, 0, v234
	v_mul_lo_u32 v230, v230, s89
	v_add3_u32 v230, v230, v229, s91
	v_add_u32_e32 v231, 8, v234
	v_mul_lo_u32 v231, v231, s89
	v_add3_u32 v231, v231, v229, s91
	v_add_u32_e32 v232, 16, v234
	v_mul_lo_u32 v232, v232, s89
	v_add3_u32 v232, v232, v229, s91
	v_add_u32_e32 v233, 24, v234
	v_mul_lo_u32 v233, v233, s89
	v_add3_u32 v233, v233, v229, s91
	s_waitcnt lgkmcnt(3)
	global_store_dwordx4 v230, v[206:209], s[96:97]
	s_waitcnt lgkmcnt(2)
	global_store_dwordx4 v231, v[212:215], s[96:97]
	s_waitcnt lgkmcnt(1)
	global_store_dwordx4 v232, v[216:219], s[96:97]
	s_waitcnt lgkmcnt(0)
	global_store_dwordx4 v233, v[220:223], s[96:97]
	v_lshlrev_b32_e32 v132, 16, v206
	v_and_b32_e32 v133, 0xffff0000, v206
	v_mul_f32_e32 v128, v132, v132
	v_fma_f32 v128, v133, v133, v128
	v_lshlrev_b32_e32 v132, 16, v207
	v_and_b32_e32 v133, 0xffff0000, v207
	v_fma_f32 v128, v132, v132, v128
	v_fma_f32 v128, v133, v133, v128
	v_lshlrev_b32_e32 v132, 16, v208
	v_and_b32_e32 v133, 0xffff0000, v208
	v_fma_f32 v128, v132, v132, v128
	v_fma_f32 v128, v133, v133, v128
	v_lshlrev_b32_e32 v132, 16, v209
	v_and_b32_e32 v133, 0xffff0000, v209
	v_fma_f32 v128, v132, v132, v128
	v_fma_f32 v128, v133, v133, v128
	v_lshlrev_b32_e32 v132, 16, v212
	v_and_b32_e32 v133, 0xffff0000, v212
	v_mul_f32_e32 v129, v132, v132
	v_fma_f32 v129, v133, v133, v129
	v_lshlrev_b32_e32 v132, 16, v213
	v_and_b32_e32 v133, 0xffff0000, v213
	v_fma_f32 v129, v132, v132, v129
	v_fma_f32 v129, v133, v133, v129
	v_lshlrev_b32_e32 v132, 16, v214
	v_and_b32_e32 v133, 0xffff0000, v214
	v_fma_f32 v129, v132, v132, v129
	v_fma_f32 v129, v133, v133, v129
	v_lshlrev_b32_e32 v132, 16, v215
	v_and_b32_e32 v133, 0xffff0000, v215
	v_fma_f32 v129, v132, v132, v129
	v_fma_f32 v129, v133, v133, v129
	v_lshlrev_b32_e32 v132, 16, v216
	v_and_b32_e32 v133, 0xffff0000, v216
	v_mul_f32_e32 v130, v132, v132
	v_fma_f32 v130, v133, v133, v130
	v_lshlrev_b32_e32 v132, 16, v217
	v_and_b32_e32 v133, 0xffff0000, v217
	v_fma_f32 v130, v132, v132, v130
	v_fma_f32 v130, v133, v133, v130
	v_lshlrev_b32_e32 v132, 16, v218
	v_and_b32_e32 v133, 0xffff0000, v218
	v_fma_f32 v130, v132, v132, v130
	v_fma_f32 v130, v133, v133, v130
	v_lshlrev_b32_e32 v132, 16, v219
	v_and_b32_e32 v133, 0xffff0000, v219
	v_fma_f32 v130, v132, v132, v130
	v_fma_f32 v130, v133, v133, v130
	v_lshlrev_b32_e32 v132, 16, v220
	v_and_b32_e32 v133, 0xffff0000, v220
	v_mul_f32_e32 v131, v132, v132
	v_fma_f32 v131, v133, v133, v131
	v_lshlrev_b32_e32 v132, 16, v221
	v_and_b32_e32 v133, 0xffff0000, v221
	v_fma_f32 v131, v132, v132, v131
	v_fma_f32 v131, v133, v133, v131
	v_lshlrev_b32_e32 v132, 16, v222
	v_and_b32_e32 v133, 0xffff0000, v222
	v_fma_f32 v131, v132, v132, v131
	v_fma_f32 v131, v133, v133, v131
	v_lshlrev_b32_e32 v132, 16, v223
	v_and_b32_e32 v133, 0xffff0000, v223
	v_fma_f32 v131, v132, v132, v131
	v_fma_f32 v131, v133, v133, v131
	s_nop 1
	v_add_f32_dpp v136, v128, v128 quad_perm:[1,0,3,2] row_mask:0xf bank_mask:0xf
	v_add_f32_dpp v137, v129, v129 quad_perm:[1,0,3,2] row_mask:0xf bank_mask:0xf
	v_add_f32_dpp v138, v130, v130 quad_perm:[1,0,3,2] row_mask:0xf bank_mask:0xf
	v_add_f32_dpp v139, v131, v131 quad_perm:[1,0,3,2] row_mask:0xf bank_mask:0xf
	v_add_f32_dpp v128, v136, v136 quad_perm:[2,3,0,1] row_mask:0xf bank_mask:0xf
	v_add_f32_dpp v129, v137, v137 quad_perm:[2,3,0,1] row_mask:0xf bank_mask:0xf
	v_add_f32_dpp v130, v138, v138 quad_perm:[2,3,0,1] row_mask:0xf bank_mask:0xf
	v_add_f32_dpp v131, v139, v139 quad_perm:[2,3,0,1] row_mask:0xf bank_mask:0xf
	v_add_f32_dpp v136, v128, v128 row_half_mirror row_mask:0xf bank_mask:0xf
	v_add_f32_dpp v137, v129, v129 row_half_mirror row_mask:0xf bank_mask:0xf
	v_add_f32_dpp v138, v130, v130 row_half_mirror row_mask:0xf bank_mask:0xf
	v_add_f32_dpp v139, v131, v131 row_half_mirror row_mask:0xf bank_mask:0xf
	v_add_f32_e32 v136, v236, v136
	v_add_f32_e32 v137, v237, v137
	v_add_f32_e32 v138, v238, v138
	v_add_f32_e32 v139, v239, v139
	v_cmp_eq_u32_e32 vcc, 0, v229
	v_add_u32_e32 v230, 0, v234
	v_lshlrev_b32_e32 v230, 2, v230
	v_add_u32_e32 v231, 8, v234
	v_lshlrev_b32_e32 v231, 2, v231
	v_add_u32_e32 v232, 16, v234
	v_lshlrev_b32_e32 v232, 2, v232
	v_add_u32_e32 v233, 24, v234
	v_lshlrev_b32_e32 v233, 2, v233
	s_and_b64 exec, exec, vcc
	global_atomic_add_f32 v230, v136, s[98:99]
	global_atomic_add_f32 v231, v137, s[98:99]
	global_atomic_add_f32 v232, v138, s[98:99]
	global_atomic_add_f32 v233, v139, s[98:99]
	s_mov_b64 exec, -1
	s_branch .Lep0_01_end

.Lep0_01_end:
.Lep0_10:
	s_add_u32 s94, s92, 32
	s_add_u32 s95, s93, 0
	s_lshr_b32 s90, s95, 6
	s_cmp_lt_u32 s90, 4
	s_cbranch_scc1 .Lep0_10_t0
	s_cmp_lt_u32 s90, 6
	s_cbranch_scc1 .Lep0_10_t4
	s_cmp_lt_u32 s90, 7
	s_cbranch_scc1 .Lep0_10_t6
	s_cmp_lt_u32 s90, 23
	s_cbranch_scc1 .Lep0_10_t7
	s_branch .Lep0_10_end

.Lep0_10_mR:
	s_load_dwordx2 s[98:99], s[0:1], 0x148
	v_add_u32_e32 v230, s94, v227
	v_lshlrev_b32_e32 v230, 8, v230
	v_add_u32_e32 v236, v230, v224
	v_mov_b32_e32 v237, 0
	s_waitcnt lgkmcnt(0)
	v_lshl_add_u64 v[236:237], s[98:99], 0, v[236:237]
	global_load_dwordx2 v[128:129], v[236:237], off
	global_load_dwordx2 v[130:131], v[236:237], off offset:256
	global_load_dwordx2 v[132:133], v[236:237], off offset:512
	global_load_dwordx2 v[134:135], v[236:237], off offset:768
	global_load_dwordx2 v[136:137], v[236:237], off offset:2048
	global_load_dwordx2 v[138:139], v[236:237], off offset:2304
	global_load_dwordx2 v[140:141], v[236:237], off offset:2560
	global_load_dwordx2 v[142:143], v[236:237], off offset:2816
	v_add_co_u32_e32 v238, vcc, 0x1000, v236
	s_nop 1
	v_addc_co_u32_e32 v239, vcc, 0, v237, vcc
	global_load_dwordx2 v[144:145], v[238:239], off
	global_load_dwordx2 v[146:147], v[238:239], off offset:256
	global_load_dwordx2 v[148:149], v[238:239], off offset:512
	global_load_dwordx2 v[150:151], v[238:239], off offset:768
	global_load_dwordx2 v[152:153], v[238:239], off offset:2048
	global_load_dwordx2 v[154:155], v[238:239], off offset:2304
	global_load_dwordx2 v[156:157], v[238:239], off offset:2560
	global_load_dwordx2 v[158:159], v[238:239], off offset:2816
	s_waitcnt vmcnt(15)
	v_mul_f32_e32 v230, v32, v129
	v_mul_f32_e32 v231, v48, v129
	v_fma_f32 v230, v48, v128, -v230
	v_fma_f32 v231, v32, v128, v231
	v_mul_f32_e32 v230, s88, v230
	v_mul_f32_e32 v231, s88, v231
	v_cvt_pk_bf16_f32 v230, v230, v231
	ds_write_b16 v225, v230
	ds_write_b16_d16_hi v225, v230 offset:64
	s_waitcnt vmcnt(14)
	v_mul_f32_e32 v230, v33, v131
	v_mul_f32_e32 v231, v49, v131
	v_fma_f32 v230, v49, v130, -v230
	v_fma_f32 v231, v33, v130, v231
	v_mul_f32_e32 v230, s88, v230
	v_mul_f32_e32 v231, s88, v231
	v_cvt_pk_bf16_f32 v230, v230, v231
	ds_write_b16 v225, v230 offset:144
	ds_write_b16_d16_hi v225, v230 offset:208
	s_waitcnt vmcnt(13)
	v_mul_f32_e32 v230, v34, v133
	v_mul_f32_e32 v231, v50, v133
	v_fma_f32 v230, v50, v132, -v230
	v_fma_f32 v231, v34, v132, v231
	v_mul_f32_e32 v230, s88, v230
	v_mul_f32_e32 v231, s88, v231
	v_cvt_pk_bf16_f32 v230, v230, v231
	ds_write_b16 v225, v230 offset:288
	ds_write_b16_d16_hi v225, v230 offset:352
	s_waitcnt vmcnt(12)
	v_mul_f32_e32 v230, v35, v135
	v_mul_f32_e32 v231, v51, v135
	v_fma_f32 v230, v51, v134, -v230
	v_fma_f32 v231, v35, v134, v231
	v_mul_f32_e32 v230, s88, v230
	v_mul_f32_e32 v231, s88, v231
	v_cvt_pk_bf16_f32 v230, v230, v231
	ds_write_b16 v225, v230 offset:432
	ds_write_b16_d16_hi v225, v230 offset:496
	s_waitcnt vmcnt(11)
	v_mul_f32_e32 v230, v36, v137
	v_mul_f32_e32 v231, v52, v137
	v_fma_f32 v230, v52, v136, -v230
	v_fma_f32 v231, v36, v136, v231
	v_mul_f32_e32 v230, s88, v230
	v_mul_f32_e32 v231, s88, v231
	v_cvt_pk_bf16_f32 v230, v230, v231
	ds_write_b16 v225, v230 offset:1152
	ds_write_b16_d16_hi v225, v230 offset:1216
	s_waitcnt vmcnt(10)
	v_mul_f32_e32 v230, v37, v139
	v_mul_f32_e32 v231, v53, v139
	v_fma_f32 v230, v53, v138, -v230
	v_fma_f32 v231, v37, v138, v231
	v_mul_f32_e32 v230, s88, v230
	v_mul_f32_e32 v231, s88, v231
	v_cvt_pk_bf16_f32 v230, v230, v231
	ds_write_b16 v225, v230 offset:1296
	ds_write_b16_d16_hi v225, v230 offset:1360
	s_waitcnt vmcnt(9)
	v_mul_f32_e32 v230, v38, v141
	v_mul_f32_e32 v231, v54, v141
	v_fma_f32 v230, v54, v140, -v230
	v_fma_f32 v231, v38, v140, v231
	v_mul_f32_e32 v230, s88, v230
	v_mul_f32_e32 v231, s88, v231
	v_cvt_pk_bf16_f32 v230, v230, v231
	ds_write_b16 v225, v230 offset:1440
	ds_write_b16_d16_hi v225, v230 offset:1504
	s_waitcnt vmcnt(8)
	v_mul_f32_e32 v230, v39, v143
	v_mul_f32_e32 v231, v55, v143
	v_fma_f32 v230, v55, v142, -v230
	v_fma_f32 v231, v39, v142, v231
	v_mul_f32_e32 v230, s88, v230
	v_mul_f32_e32 v231, s88, v231
	v_cvt_pk_bf16_f32 v230, v230, v231
	ds_write_b16 v225, v230 offset:1584
	ds_write_b16_d16_hi v225, v230 offset:1648
	s_waitcnt vmcnt(7)
	v_mul_f32_e32 v230, v40, v145
	v_mul_f32_e32 v231, v56, v145
	v_fma_f32 v230, v56, v144, -v230
	v_fma_f32 v231, v40, v144, v231
	v_mul_f32_e32 v230, s88, v230
	v_mul_f32_e32 v231, s88, v231
	v_cvt_pk_bf16_f32 v230, v230, v231
	ds_write_b16 v225, v230 offset:2304
	ds_write_b16_d16_hi v225, v230 offset:2368
	s_waitcnt vmcnt(6)
	v_mul_f32_e32 v230, v41, v147
	v_mul_f32_e32 v231, v57, v147
	v_fma_f32 v230, v57, v146, -v230
	v_fma_f32 v231, v41, v146, v231
	v_mul_f32_e32 v230, s88, v230
	v_mul_f32_e32 v231, s88, v231
	v_cvt_pk_bf16_f32 v230, v230, v231
	ds_write_b16 v225, v230 offset:2448
	ds_write_b16_d16_hi v225, v230 offset:2512
	s_waitcnt vmcnt(5)
	v_mul_f32_e32 v230, v42, v149
	v_mul_f32_e32 v231, v58, v149
	v_fma_f32 v230, v58, v148, -v230
	v_fma_f32 v231, v42, v148, v231
	v_mul_f32_e32 v230, s88, v230
	v_mul_f32_e32 v231, s88, v231
	v_cvt_pk_bf16_f32 v230, v230, v231
	ds_write_b16 v225, v230 offset:2592
	ds_write_b16_d16_hi v225, v230 offset:2656
	s_waitcnt vmcnt(4)
	v_mul_f32_e32 v230, v43, v151
	v_mul_f32_e32 v231, v59, v151
	v_fma_f32 v230, v59, v150, -v230
	v_fma_f32 v231, v43, v150, v231
	v_mul_f32_e32 v230, s88, v230
	v_mul_f32_e32 v231, s88, v231
	v_cvt_pk_bf16_f32 v230, v230, v231
	ds_write_b16 v225, v230 offset:2736
	ds_write_b16_d16_hi v225, v230 offset:2800
	s_waitcnt vmcnt(3)
	v_mul_f32_e32 v230, v44, v153
	v_mul_f32_e32 v231, v60, v153
	v_fma_f32 v230, v60, v152, -v230
	v_fma_f32 v231, v44, v152, v231
	v_mul_f32_e32 v230, s88, v230
	v_mul_f32_e32 v231, s88, v231
	v_cvt_pk_bf16_f32 v230, v230, v231
	ds_write_b16 v225, v230 offset:3456
	ds_write_b16_d16_hi v225, v230 offset:3520
	s_waitcnt vmcnt(2)
	v_mul_f32_e32 v230, v45, v155
	v_mul_f32_e32 v231, v61, v155
	v_fma_f32 v230, v61, v154, -v230
	v_fma_f32 v231, v45, v154, v231
	v_mul_f32_e32 v230, s88, v230
	v_mul_f32_e32 v231, s88, v231
	v_cvt_pk_bf16_f32 v230, v230, v231
	ds_write_b16 v225, v230 offset:3600
	ds_write_b16_d16_hi v225, v230 offset:3664
	s_waitcnt vmcnt(1)
	v_mul_f32_e32 v230, v46, v157
	v_mul_f32_e32 v231, v62, v157
	v_fma_f32 v230, v62, v156, -v230
	v_fma_f32 v231, v46, v156, v231
	v_mul_f32_e32 v230, s88, v230
	v_mul_f32_e32 v231, s88, v231
	v_cvt_pk_bf16_f32 v230, v230, v231
	ds_write_b16 v225, v230 offset:3744
	ds_write_b16_d16_hi v225, v230 offset:3808
	s_waitcnt vmcnt(0)
	v_mul_f32_e32 v230, v47, v159
	v_mul_f32_e32 v231, v63, v159
	v_fma_f32 v230, v63, v158, -v230
	v_fma_f32 v231, v47, v158, v231
	v_mul_f32_e32 v230, s88, v230
	v_mul_f32_e32 v231, s88, v231
	v_cvt_pk_bf16_f32 v230, v230, v231
	ds_write_b16 v225, v230 offset:3888
	ds_write_b16_d16_hi v225, v230 offset:3952
	s_branch .Lep0_10_stb

.Lep0_10_end:
.Lep0_11:
	s_add_u32 s94, s92, 32
	s_add_u32 s95, s93, 64
	s_lshr_b32 s90, s95, 6
	s_cmp_lt_u32 s90, 4
	s_cbranch_scc1 .Lep0_11_t0
	s_cmp_lt_u32 s90, 6
	s_cbranch_scc1 .Lep0_11_t4
	s_cmp_lt_u32 s90, 7
	s_cbranch_scc1 .Lep0_11_t6
	s_cmp_lt_u32 s90, 23
	s_cbranch_scc1 .Lep0_11_t7
	s_branch .Lep0_11_end

.Lep0_11_mR:
	s_load_dwordx2 s[98:99], s[0:1], 0x148
	v_add_u32_e32 v230, s94, v227
	v_lshlrev_b32_e32 v230, 8, v230
	v_add_u32_e32 v236, v230, v224
	v_mov_b32_e32 v237, 0
	s_waitcnt lgkmcnt(0)
	v_lshl_add_u64 v[236:237], s[98:99], 0, v[236:237]
	global_load_dwordx2 v[128:129], v[236:237], off
	global_load_dwordx2 v[130:131], v[236:237], off offset:256
	global_load_dwordx2 v[132:133], v[236:237], off offset:512
	global_load_dwordx2 v[134:135], v[236:237], off offset:768
	global_load_dwordx2 v[136:137], v[236:237], off offset:2048
	global_load_dwordx2 v[138:139], v[236:237], off offset:2304
	global_load_dwordx2 v[140:141], v[236:237], off offset:2560
	global_load_dwordx2 v[142:143], v[236:237], off offset:2816
	v_add_co_u32_e32 v238, vcc, 0x1000, v236
	s_nop 1
	v_addc_co_u32_e32 v239, vcc, 0, v237, vcc
	global_load_dwordx2 v[144:145], v[238:239], off
	global_load_dwordx2 v[146:147], v[238:239], off offset:256
	global_load_dwordx2 v[148:149], v[238:239], off offset:512
	global_load_dwordx2 v[150:151], v[238:239], off offset:768
	global_load_dwordx2 v[152:153], v[238:239], off offset:2048
	global_load_dwordx2 v[154:155], v[238:239], off offset:2304
	global_load_dwordx2 v[156:157], v[238:239], off offset:2560
	global_load_dwordx2 v[158:159], v[238:239], off offset:2816
	s_waitcnt vmcnt(15)
	v_mul_f32_e32 v230, v0, v129
	v_mul_f32_e32 v231, v16, v129
	v_fma_f32 v230, v16, v128, -v230
	v_fma_f32 v231, v0, v128, v231
	v_mul_f32_e32 v230, s88, v230
	v_mul_f32_e32 v231, s88, v231
	v_cvt_pk_bf16_f32 v230, v230, v231
	ds_write_b16 v225, v230
	ds_write_b16_d16_hi v225, v230 offset:64
	s_waitcnt vmcnt(14)
	v_mul_f32_e32 v230, v1, v131
	v_mul_f32_e32 v231, v17, v131
	v_fma_f32 v230, v17, v130, -v230
	v_fma_f32 v231, v1, v130, v231
	v_mul_f32_e32 v230, s88, v230
	v_mul_f32_e32 v231, s88, v231
	v_cvt_pk_bf16_f32 v230, v230, v231
	ds_write_b16 v225, v230 offset:144
	ds_write_b16_d16_hi v225, v230 offset:208
	s_waitcnt vmcnt(13)
	v_mul_f32_e32 v230, v2, v133
	v_mul_f32_e32 v231, v18, v133
	v_fma_f32 v230, v18, v132, -v230
	v_fma_f32 v231, v2, v132, v231
	v_mul_f32_e32 v230, s88, v230
	v_mul_f32_e32 v231, s88, v231
	v_cvt_pk_bf16_f32 v230, v230, v231
	ds_write_b16 v225, v230 offset:288
	ds_write_b16_d16_hi v225, v230 offset:352
	s_waitcnt vmcnt(12)
	v_mul_f32_e32 v230, v3, v135
	v_mul_f32_e32 v231, v19, v135
	v_fma_f32 v230, v19, v134, -v230
	v_fma_f32 v231, v3, v134, v231
	v_mul_f32_e32 v230, s88, v230
	v_mul_f32_e32 v231, s88, v231
	v_cvt_pk_bf16_f32 v230, v230, v231
	ds_write_b16 v225, v230 offset:432
	ds_write_b16_d16_hi v225, v230 offset:496
	s_waitcnt vmcnt(11)
	v_mul_f32_e32 v230, v4, v137
	v_mul_f32_e32 v231, v20, v137
	v_fma_f32 v230, v20, v136, -v230
	v_fma_f32 v231, v4, v136, v231
	v_mul_f32_e32 v230, s88, v230
	v_mul_f32_e32 v231, s88, v231
	v_cvt_pk_bf16_f32 v230, v230, v231
	ds_write_b16 v225, v230 offset:1152
	ds_write_b16_d16_hi v225, v230 offset:1216
	s_waitcnt vmcnt(10)
	v_mul_f32_e32 v230, v5, v139
	v_mul_f32_e32 v231, v21, v139
	v_fma_f32 v230, v21, v138, -v230
	v_fma_f32 v231, v5, v138, v231
	v_mul_f32_e32 v230, s88, v230
	v_mul_f32_e32 v231, s88, v231
	v_cvt_pk_bf16_f32 v230, v230, v231
	ds_write_b16 v225, v230 offset:1296
	ds_write_b16_d16_hi v225, v230 offset:1360
	s_waitcnt vmcnt(9)
	v_mul_f32_e32 v230, v6, v141
	v_mul_f32_e32 v231, v22, v141
	v_fma_f32 v230, v22, v140, -v230
	v_fma_f32 v231, v6, v140, v231
	v_mul_f32_e32 v230, s88, v230
	v_mul_f32_e32 v231, s88, v231
	v_cvt_pk_bf16_f32 v230, v230, v231
	ds_write_b16 v225, v230 offset:1440
	ds_write_b16_d16_hi v225, v230 offset:1504
	s_waitcnt vmcnt(8)
	v_mul_f32_e32 v230, v7, v143
	v_mul_f32_e32 v231, v23, v143
	v_fma_f32 v230, v23, v142, -v230
	v_fma_f32 v231, v7, v142, v231
	v_mul_f32_e32 v230, s88, v230
	v_mul_f32_e32 v231, s88, v231
	v_cvt_pk_bf16_f32 v230, v230, v231
	ds_write_b16 v225, v230 offset:1584
	ds_write_b16_d16_hi v225, v230 offset:1648
	s_waitcnt vmcnt(7)
	v_mul_f32_e32 v230, v8, v145
	v_mul_f32_e32 v231, v24, v145
	v_fma_f32 v230, v24, v144, -v230
	v_fma_f32 v231, v8, v144, v231
	v_mul_f32_e32 v230, s88, v230
	v_mul_f32_e32 v231, s88, v231
	v_cvt_pk_bf16_f32 v230, v230, v231
	ds_write_b16 v225, v230 offset:2304
	ds_write_b16_d16_hi v225, v230 offset:2368
	s_waitcnt vmcnt(6)
	v_mul_f32_e32 v230, v9, v147
	v_mul_f32_e32 v231, v25, v147
	v_fma_f32 v230, v25, v146, -v230
	v_fma_f32 v231, v9, v146, v231
	v_mul_f32_e32 v230, s88, v230
	v_mul_f32_e32 v231, s88, v231
	v_cvt_pk_bf16_f32 v230, v230, v231
	ds_write_b16 v225, v230 offset:2448
	ds_write_b16_d16_hi v225, v230 offset:2512
	s_waitcnt vmcnt(5)
	v_mul_f32_e32 v230, v10, v149
	v_mul_f32_e32 v231, v26, v149
	v_fma_f32 v230, v26, v148, -v230
	v_fma_f32 v231, v10, v148, v231
	v_mul_f32_e32 v230, s88, v230
	v_mul_f32_e32 v231, s88, v231
	v_cvt_pk_bf16_f32 v230, v230, v231
	ds_write_b16 v225, v230 offset:2592
	ds_write_b16_d16_hi v225, v230 offset:2656
	s_waitcnt vmcnt(4)
	v_mul_f32_e32 v230, v11, v151
	v_mul_f32_e32 v231, v27, v151
	v_fma_f32 v230, v27, v150, -v230
	v_fma_f32 v231, v11, v150, v231
	v_mul_f32_e32 v230, s88, v230
	v_mul_f32_e32 v231, s88, v231
	v_cvt_pk_bf16_f32 v230, v230, v231
	ds_write_b16 v225, v230 offset:2736
	ds_write_b16_d16_hi v225, v230 offset:2800
	s_waitcnt vmcnt(3)
	v_mul_f32_e32 v230, v12, v153
	v_mul_f32_e32 v231, v28, v153
	v_fma_f32 v230, v28, v152, -v230
	v_fma_f32 v231, v12, v152, v231
	v_mul_f32_e32 v230, s88, v230
	v_mul_f32_e32 v231, s88, v231
	v_cvt_pk_bf16_f32 v230, v230, v231
	ds_write_b16 v225, v230 offset:3456
	ds_write_b16_d16_hi v225, v230 offset:3520
	s_waitcnt vmcnt(2)
	v_mul_f32_e32 v230, v13, v155
	v_mul_f32_e32 v231, v29, v155
	v_fma_f32 v230, v29, v154, -v230
	v_fma_f32 v231, v13, v154, v231
	v_mul_f32_e32 v230, s88, v230
	v_mul_f32_e32 v231, s88, v231
	v_cvt_pk_bf16_f32 v230, v230, v231
	ds_write_b16 v225, v230 offset:3600
	ds_write_b16_d16_hi v225, v230 offset:3664
	s_waitcnt vmcnt(1)
	v_mul_f32_e32 v230, v14, v157
	v_mul_f32_e32 v231, v30, v157
	v_fma_f32 v230, v30, v156, -v230
	v_fma_f32 v231, v14, v156, v231
	v_mul_f32_e32 v230, s88, v230
	v_mul_f32_e32 v231, s88, v231
	v_cvt_pk_bf16_f32 v230, v230, v231
	ds_write_b16 v225, v230 offset:3744
	ds_write_b16_d16_hi v225, v230 offset:3808
	s_waitcnt vmcnt(0)
	v_mul_f32_e32 v230, v15, v159
	v_mul_f32_e32 v231, v31, v159
	v_fma_f32 v230, v31, v158, -v230
	v_fma_f32 v231, v15, v158, v231
	v_mul_f32_e32 v230, s88, v230
	v_mul_f32_e32 v231, s88, v231
	v_cvt_pk_bf16_f32 v230, v230, v231
	ds_write_b16 v225, v230 offset:3888
	ds_write_b16_d16_hi v225, v230 offset:3952
	s_branch .Lep0_11_stb

.Lep0_11_end:
	s_branch .LBB0_302
.LBB0_811:
	s_cmp_lt_i32 s45, 4
	s_cbranch_scc1 .LBB0_865
	s_waitcnt vmcnt(0)
	v_cmp_eq_u32_e32 vcc, 0, v188
	s_waitcnt lgkmcnt(0)
	s_and_b64 s[4:5], s[46:47], vcc
	s_waitcnt vmcnt(63) expcnt(7) lgkmcnt(15)
	s_barrier
	s_and_saveexec_b64 s[2:3], s[4:5]
	s_cbranch_execz .LBB0_864
	v_mov_b32_e32 v0, 0x24400
	s_waitcnt vmcnt(0) expcnt(0) lgkmcnt(0)
	ds_read_b32 v2, v0
	v_mov_b32_e32 v0, 0x24404
	ds_read_b32 v0, v0
	s_waitcnt lgkmcnt(1)
	v_cmp_ne_u32_e32 vcc, 0, v2
	s_cbranch_vccnz .LBB0_828
	s_add_u32 s4, s40, 0x1000
	s_addc_u32 s5, s41, 0
	s_add_u32 s6, s40, 0x1100
	s_addc_u32 s7, s41, 0
	s_add_u32 s8, s40, 0x1200
	s_addc_u32 s9, s41, 0
	s_mul_i32 s18, s43, s33
	s_add_u32 s10, s40, 0x1300
	s_mul_i32 s18, s18, s42
	s_addc_u32 s11, s41, 0
	s_mov_b32 s19, 1
	v_mov_b32_e32 v16, 0
	s_branch .LBB0_816

.LBB0_1470:
	ds_read_b128 v[128:131], v233
	ds_read_b128 v[136:139], v237
	ds_read_b128 v[132:135], v233 offset:4096
	ds_read_b128 v[140:143], v237 offset:4096
	ds_read_b128 v[144:147], v237 offset:8192
	ds_read_b128 v[148:151], v237 offset:12288
	s_waitcnt lgkmcnt(6)
	v_mfma_f32_32x32x16_bf16 v[112:127], v[188:191], v[216:219], v[112:127]
	v_mfma_f32_32x32x16_bf16 v[48:63], v[212:215], v[216:219], v[48:63]
	v_mfma_f32_32x32x16_bf16 v[96:111], v[188:191], v[220:223], v[96:111]
	v_mfma_f32_32x32x16_bf16 v[32:47], v[212:215], v[220:223], v[32:47]
	v_mfma_f32_32x32x16_bf16 v[80:95], v[188:191], v[224:227], v[80:95]
	v_mfma_f32_32x32x16_bf16 v[16:31], v[212:215], v[224:227], v[16:31]
	v_mfma_f32_32x32x16_bf16 v[64:79], v[188:191], v[228:231], v[64:79]
	v_mfma_f32_32x32x16_bf16 v[0:15], v[212:215], v[228:231], v[0:15]
	ds_read_b128 v[188:191], v234
	ds_read_b128 v[216:219], v238
	ds_read_b128 v[212:215], v234 offset:4096
	ds_read_b128 v[220:223], v238 offset:4096
	ds_read_b128 v[224:227], v238 offset:8192
	ds_read_b128 v[228:231], v238 offset:12288
	s_waitcnt lgkmcnt(6)
	v_mfma_f32_32x32x16_bf16 v[112:127], v[128:131], v[136:139], v[112:127]
	v_mfma_f32_32x32x16_bf16 v[48:63], v[132:135], v[136:139], v[48:63]
	v_mfma_f32_32x32x16_bf16 v[96:111], v[128:131], v[140:143], v[96:111]
	v_mfma_f32_32x32x16_bf16 v[32:47], v[132:135], v[140:143], v[32:47]
	v_mfma_f32_32x32x16_bf16 v[80:95], v[128:131], v[144:147], v[80:95]
	v_mfma_f32_32x32x16_bf16 v[16:31], v[132:135], v[144:147], v[16:31]
	v_mfma_f32_32x32x16_bf16 v[64:79], v[128:131], v[148:151], v[64:79]
	v_mfma_f32_32x32x16_bf16 v[0:15], v[132:135], v[148:151], v[0:15]
	ds_read_b128 v[128:131], v235
	ds_read_b128 v[136:139], v239
	ds_read_b128 v[132:135], v235 offset:4096
	ds_read_b128 v[140:143], v239 offset:4096
	ds_read_b128 v[144:147], v239 offset:8192
	ds_read_b128 v[148:151], v239 offset:12288
	s_waitcnt lgkmcnt(6)
	v_mfma_f32_32x32x16_bf16 v[112:127], v[188:191], v[216:219], v[112:127]
	v_mfma_f32_32x32x16_bf16 v[48:63], v[212:215], v[216:219], v[48:63]
	v_mfma_f32_32x32x16_bf16 v[96:111], v[188:191], v[220:223], v[96:111]
	v_mfma_f32_32x32x16_bf16 v[32:47], v[212:215], v[220:223], v[32:47]
	v_mfma_f32_32x32x16_bf16 v[80:95], v[188:191], v[224:227], v[80:95]
	v_mfma_f32_32x32x16_bf16 v[16:31], v[212:215], v[224:227], v[16:31]
	v_mfma_f32_32x32x16_bf16 v[64:79], v[188:191], v[228:231], v[64:79]
	v_mfma_f32_32x32x16_bf16 v[0:15], v[212:215], v[228:231], v[0:15]
	s_waitcnt vmcnt(0) lgkmcnt(0)
	s_barrier
	v_xor_b32_e32 v232, 0x10000, v232
	v_xor_b32_e32 v236, 0x10000, v236
	v_mfma_f32_32x32x16_bf16 v[112:127], v[128:131], v[136:139], v[112:127]
	v_xor_b32_e32 v233, 0x10000, v233
	v_xor_b32_e32 v237, 0x10000, v237
	v_mfma_f32_32x32x16_bf16 v[48:63], v[132:135], v[136:139], v[48:63]
	v_xor_b32_e32 v234, 0x10000, v234
	v_xor_b32_e32 v238, 0x10000, v238
	v_mfma_f32_32x32x16_bf16 v[96:111], v[128:131], v[140:143], v[96:111]
	v_xor_b32_e32 v235, 0x10000, v235
	v_xor_b32_e32 v239, 0x10000, v239
	v_mfma_f32_32x32x16_bf16 v[32:47], v[132:135], v[140:143], v[32:47]
	v_mfma_f32_32x32x16_bf16 v[80:95], v[128:131], v[144:147], v[80:95]
	v_mfma_f32_32x32x16_bf16 v[16:31], v[132:135], v[144:147], v[16:31]
	v_mfma_f32_32x32x16_bf16 v[64:79], v[128:131], v[148:151], v[64:79]
	v_mfma_f32_32x32x16_bf16 v[0:15], v[132:135], v[148:151], v[0:15]
	v_mbcnt_hi_u32_b32 v230, -1, v210
	v_and_b32_e32 v231, 31, v230
	v_lshrrev_b32_e32 v232, 5, v230
	v_lshlrev_b32_e32 v224, 3, v231
	v_lshlrev_b32_e32 v227, 2, v232
	s_lshr_b32 s90, s70, 6
	s_mul_i32 s91, s90, 0x1200
	s_add_u32 s91, s91, 0x12000
	v_mul_u32_u24_e32 v233, 0x240, v232
	v_lshl_add_u32 v233, v231, 1, v233
	v_add_u32_e32 v225, s91, v233
	v_lshrrev_b32_e32 v228, 3, v230
	v_and_b32_e32 v234, 7, v230
	v_lshlrev_b32_e32 v229, 4, v234
	v_mul_u32_u24_e32 v233, 0x90, v228
	v_add3_u32 v226, v233, v229, s91
	s_mul_i32 s92, s4, 9
	s_sub_u32 s93, s8, s92
	s_lshl_b32 s93, s93, 8
	s_lshl_b32 s92, s4, 8
	s_lshr_b32 s94, s90, 1
	s_lshl_b32 s94, s94, 6
	s_add_u32 s92, s92, s94
	s_and_b32 s94, s90, 1
	s_lshl_b32 s94, s94, 7
	s_add_u32 s93, s93, s94
.Lep2_00:
	s_add_u32 s94, s92, 0
	s_add_u32 s95, s93, 0
	s_lshr_b32 s90, s95, 6
	s_cmp_lt_u32 s90, 16
	s_cbranch_scc1 .Lep2_00_t0
	s_cmp_lt_u32 s90, 18
	s_cbranch_scc1 .Lep2_00_t16
	s_cmp_lt_u32 s90, 20
	s_cbranch_scc1 .Lep2_00_t18
	s_cmp_lt_u32 s90, 36
	s_cbranch_scc1 .Lep2_00_t20
	s_branch .Lep2_00_end

.LBB0_2413:
	ds_read_b128 v[128:131], v229
	ds_read_b128 v[136:139], v233
	ds_read_b128 v[132:135], v229 offset:4096
	ds_read_b128 v[140:143], v233 offset:4096
	ds_read_b128 v[144:147], v233 offset:8192
	ds_read_b128 v[148:151], v233 offset:12288
	s_waitcnt lgkmcnt(6)
	v_mfma_f32_32x32x16_bf16 v[112:127], v[202:205], v[212:215], v[112:127]
	v_mfma_f32_32x32x16_bf16 v[48:63], v[206:209], v[212:215], v[48:63]
	v_mfma_f32_32x32x16_bf16 v[96:111], v[202:205], v[216:219], v[96:111]
	v_mfma_f32_32x32x16_bf16 v[32:47], v[206:209], v[216:219], v[32:47]
	v_mfma_f32_32x32x16_bf16 v[80:95], v[202:205], v[220:223], v[80:95]
	v_mfma_f32_32x32x16_bf16 v[16:31], v[206:209], v[220:223], v[16:31]
	v_mfma_f32_32x32x16_bf16 v[64:79], v[202:205], v[224:227], v[64:79]
	v_mfma_f32_32x32x16_bf16 v[0:15], v[206:209], v[224:227], v[0:15]
	ds_read_b128 v[202:205], v230
	ds_read_b128 v[212:215], v234
	ds_read_b128 v[206:209], v230 offset:4096
	ds_read_b128 v[216:219], v234 offset:4096
	ds_read_b128 v[220:223], v234 offset:8192
	ds_read_b128 v[224:227], v234 offset:12288
	s_waitcnt lgkmcnt(6)
	v_mfma_f32_32x32x16_bf16 v[112:127], v[128:131], v[136:139], v[112:127]
	v_mfma_f32_32x32x16_bf16 v[48:63], v[132:135], v[136:139], v[48:63]
	v_mfma_f32_32x32x16_bf16 v[96:111], v[128:131], v[140:143], v[96:111]
	v_mfma_f32_32x32x16_bf16 v[32:47], v[132:135], v[140:143], v[32:47]
	v_mfma_f32_32x32x16_bf16 v[80:95], v[128:131], v[144:147], v[80:95]
	v_mfma_f32_32x32x16_bf16 v[16:31], v[132:135], v[144:147], v[16:31]
	v_mfma_f32_32x32x16_bf16 v[64:79], v[128:131], v[148:151], v[64:79]
	v_mfma_f32_32x32x16_bf16 v[0:15], v[132:135], v[148:151], v[0:15]
	ds_read_b128 v[128:131], v231
	ds_read_b128 v[136:139], v235
	ds_read_b128 v[132:135], v231 offset:4096
	ds_read_b128 v[140:143], v235 offset:4096
	ds_read_b128 v[144:147], v235 offset:8192
	ds_read_b128 v[148:151], v235 offset:12288
	s_waitcnt lgkmcnt(6)
	v_mfma_f32_32x32x16_bf16 v[112:127], v[202:205], v[212:215], v[112:127]
	v_mfma_f32_32x32x16_bf16 v[48:63], v[206:209], v[212:215], v[48:63]
	v_mfma_f32_32x32x16_bf16 v[96:111], v[202:205], v[216:219], v[96:111]
	v_mfma_f32_32x32x16_bf16 v[32:47], v[206:209], v[216:219], v[32:47]
	v_mfma_f32_32x32x16_bf16 v[80:95], v[202:205], v[220:223], v[80:95]
	v_mfma_f32_32x32x16_bf16 v[16:31], v[206:209], v[220:223], v[16:31]
	v_mfma_f32_32x32x16_bf16 v[64:79], v[202:205], v[224:227], v[64:79]
	v_mfma_f32_32x32x16_bf16 v[0:15], v[206:209], v[224:227], v[0:15]
	s_waitcnt vmcnt(0) lgkmcnt(0)
	s_barrier
	v_xor_b32_e32 v228, 0x10000, v228
	v_xor_b32_e32 v232, 0x10000, v232
	v_mfma_f32_32x32x16_bf16 v[112:127], v[128:131], v[136:139], v[112:127]
	v_xor_b32_e32 v229, 0x10000, v229
	v_xor_b32_e32 v233, 0x10000, v233
	v_mfma_f32_32x32x16_bf16 v[48:63], v[132:135], v[136:139], v[48:63]
	v_xor_b32_e32 v230, 0x10000, v230
	v_xor_b32_e32 v234, 0x10000, v234
	v_mfma_f32_32x32x16_bf16 v[96:111], v[128:131], v[140:143], v[96:111]
	v_xor_b32_e32 v231, 0x10000, v231
	v_xor_b32_e32 v235, 0x10000, v235
	v_mfma_f32_32x32x16_bf16 v[32:47], v[132:135], v[140:143], v[32:47]
	v_mfma_f32_32x32x16_bf16 v[80:95], v[128:131], v[144:147], v[80:95]
	v_mfma_f32_32x32x16_bf16 v[16:31], v[132:135], v[144:147], v[16:31]
	v_mfma_f32_32x32x16_bf16 v[64:79], v[128:131], v[148:151], v[64:79]
	v_mfma_f32_32x32x16_bf16 v[0:15], v[132:135], v[148:151], v[0:15]
	v_mbcnt_hi_u32_b32 v226, -1, v210
	v_and_b32_e32 v227, 31, v226
	v_lshrrev_b32_e32 v228, 5, v226
	v_lshlrev_b32_e32 v220, 3, v227
	v_lshlrev_b32_e32 v223, 2, v228
	s_lshr_b32 s90, s70, 6
	s_mul_i32 s91, s90, 0x1200
	s_add_u32 s91, s91, 0x12000
	v_mul_u32_u24_e32 v229, 0x240, v228
	v_lshl_add_u32 v229, v227, 1, v229
	v_add_u32_e32 v221, s91, v229
	v_lshrrev_b32_e32 v224, 3, v226
	v_and_b32_e32 v230, 7, v226
	v_lshlrev_b32_e32 v225, 4, v230
	v_mul_u32_u24_e32 v229, 0x90, v224
	v_add3_u32 v222, v229, v225, s91
	s_mul_i32 s92, s5, 15
	s_sub_u32 s93, s4, s92
	s_lshl_b32 s93, s93, 8
	s_lshl_b32 s92, s5, 8
	s_lshr_b32 s94, s90, 1
	s_lshl_b32 s94, s94, 6
	s_add_u32 s92, s92, s94
	s_and_b32 s94, s90, 1
	s_lshl_b32 s94, s94, 7
	s_add_u32 s93, s93, s94
.Lep4_00:
	s_add_u32 s94, s92, 0
	s_add_u32 s95, s93, 0
	s_lshr_b32 s90, s95, 6
	s_cmp_lt_u32 s90, 16
	s_cbranch_scc1 .Lep4_00_t0
	s_cmp_lt_u32 s90, 20
	s_cbranch_scc1 .Lep4_00_t16
	s_cmp_lt_u32 s90, 24
	s_cbranch_scc1 .Lep4_00_t20
	s_cmp_lt_u32 s90, 28
	s_cbranch_scc1 .Lep4_00_t24
	s_cmp_lt_u32 s90, 32
	s_cbranch_scc1 .Lep4_00_t28
	s_cmp_lt_u32 s90, 36
	s_cbranch_scc1 .Lep4_00_t32
	s_cmp_lt_u32 s90, 40
	s_cbranch_scc1 .Lep4_00_t36
	s_cmp_lt_u32 s90, 56
	s_cbranch_scc1 .Lep4_00_t40
	s_cmp_lt_u32 s90, 57
	s_cbranch_scc1 .Lep4_00_t56
	s_branch .Lep4_00_end

.Lep4_00_mR:
	s_load_dwordx2 s[98:99], s[0:1], 0x148
	v_add_u32_e32 v226, s94, v223
	v_lshlrev_b32_e32 v226, 8, v226
	v_add_u32_e32 v232, v226, v220
	v_mov_b32_e32 v233, 0
	s_waitcnt lgkmcnt(0)
	v_lshl_add_u64 v[232:233], s[98:99], 0, v[232:233]
	global_load_dwordx2 v[128:129], v[232:233], off
	global_load_dwordx2 v[130:131], v[232:233], off offset:256
	global_load_dwordx2 v[132:133], v[232:233], off offset:512
	global_load_dwordx2 v[134:135], v[232:233], off offset:768
	global_load_dwordx2 v[136:137], v[232:233], off offset:2048
	global_load_dwordx2 v[138:139], v[232:233], off offset:2304
	global_load_dwordx2 v[140:141], v[232:233], off offset:2560
	global_load_dwordx2 v[142:143], v[232:233], off offset:2816
	v_add_co_u32_e32 v234, vcc, 0x1000, v232
	s_nop 1
	v_addc_co_u32_e32 v235, vcc, 0, v233, vcc
	global_load_dwordx2 v[144:145], v[234:235], off
	global_load_dwordx2 v[146:147], v[234:235], off offset:256
	global_load_dwordx2 v[148:149], v[234:235], off offset:512
	global_load_dwordx2 v[150:151], v[234:235], off offset:768
	global_load_dwordx2 v[152:153], v[234:235], off offset:2048
	global_load_dwordx2 v[154:155], v[234:235], off offset:2304
	global_load_dwordx2 v[156:157], v[234:235], off offset:2560
	global_load_dwordx2 v[158:159], v[234:235], off offset:2816
	s_waitcnt vmcnt(15)
	v_mul_f32_e32 v226, v96, v129
	v_mul_f32_e32 v227, v112, v129
	v_fma_f32 v226, v112, v128, -v226
	v_fma_f32 v227, v96, v128, v227
	v_mul_f32_e32 v226, s88, v226
	v_mul_f32_e32 v227, s88, v227
	v_cvt_pk_bf16_f32 v226, v226, v227
	ds_write_b16 v221, v226
	ds_write_b16_d16_hi v221, v226 offset:64
	s_waitcnt vmcnt(14)
	v_mul_f32_e32 v226, v97, v131
	v_mul_f32_e32 v227, v113, v131
	v_fma_f32 v226, v113, v130, -v226
	v_fma_f32 v227, v97, v130, v227
	v_mul_f32_e32 v226, s88, v226
	v_mul_f32_e32 v227, s88, v227
	v_cvt_pk_bf16_f32 v226, v226, v227
	ds_write_b16 v221, v226 offset:144
	ds_write_b16_d16_hi v221, v226 offset:208
	s_waitcnt vmcnt(13)
	v_mul_f32_e32 v226, v98, v133
	v_mul_f32_e32 v227, v114, v133
	v_fma_f32 v226, v114, v132, -v226
	v_fma_f32 v227, v98, v132, v227
	v_mul_f32_e32 v226, s88, v226
	v_mul_f32_e32 v227, s88, v227
	v_cvt_pk_bf16_f32 v226, v226, v227
	ds_write_b16 v221, v226 offset:288
	ds_write_b16_d16_hi v221, v226 offset:352
	s_waitcnt vmcnt(12)
	v_mul_f32_e32 v226, v99, v135
	v_mul_f32_e32 v227, v115, v135
	v_fma_f32 v226, v115, v134, -v226
	v_fma_f32 v227, v99, v134, v227
	v_mul_f32_e32 v226, s88, v226
	v_mul_f32_e32 v227, s88, v227
	v_cvt_pk_bf16_f32 v226, v226, v227
	ds_write_b16 v221, v226 offset:432
	ds_write_b16_d16_hi v221, v226 offset:496
	s_waitcnt vmcnt(11)
	v_mul_f32_e32 v226, v100, v137
	v_mul_f32_e32 v227, v116, v137
	v_fma_f32 v226, v116, v136, -v226
	v_fma_f32 v227, v100, v136, v227
	v_mul_f32_e32 v226, s88, v226
	v_mul_f32_e32 v227, s88, v227
	v_cvt_pk_bf16_f32 v226, v226, v227
	ds_write_b16 v221, v226 offset:1152
	ds_write_b16_d16_hi v221, v226 offset:1216
	s_waitcnt vmcnt(10)
	v_mul_f32_e32 v226, v101, v139
	v_mul_f32_e32 v227, v117, v139
	v_fma_f32 v226, v117, v138, -v226
	v_fma_f32 v227, v101, v138, v227
	v_mul_f32_e32 v226, s88, v226
	v_mul_f32_e32 v227, s88, v227
	v_cvt_pk_bf16_f32 v226, v226, v227
	ds_write_b16 v221, v226 offset:1296
	ds_write_b16_d16_hi v221, v226 offset:1360
	s_waitcnt vmcnt(9)
	v_mul_f32_e32 v226, v102, v141
	v_mul_f32_e32 v227, v118, v141
	v_fma_f32 v226, v118, v140, -v226
	v_fma_f32 v227, v102, v140, v227
	v_mul_f32_e32 v226, s88, v226
	v_mul_f32_e32 v227, s88, v227
	v_cvt_pk_bf16_f32 v226, v226, v227
	ds_write_b16 v221, v226 offset:1440
	ds_write_b16_d16_hi v221, v226 offset:1504
	s_waitcnt vmcnt(8)
	v_mul_f32_e32 v226, v103, v143
	v_mul_f32_e32 v227, v119, v143
	v_fma_f32 v226, v119, v142, -v226
	v_fma_f32 v227, v103, v142, v227
	v_mul_f32_e32 v226, s88, v226
	v_mul_f32_e32 v227, s88, v227
	v_cvt_pk_bf16_f32 v226, v226, v227
	ds_write_b16 v221, v226 offset:1584
	ds_write_b16_d16_hi v221, v226 offset:1648
	s_waitcnt vmcnt(7)
	v_mul_f32_e32 v226, v104, v145
	v_mul_f32_e32 v227, v120, v145
	v_fma_f32 v226, v120, v144, -v226
	v_fma_f32 v227, v104, v144, v227
	v_mul_f32_e32 v226, s88, v226
	v_mul_f32_e32 v227, s88, v227
	v_cvt_pk_bf16_f32 v226, v226, v227
	ds_write_b16 v221, v226 offset:2304
	ds_write_b16_d16_hi v221, v226 offset:2368
	s_waitcnt vmcnt(6)
	v_mul_f32_e32 v226, v105, v147
	v_mul_f32_e32 v227, v121, v147
	v_fma_f32 v226, v121, v146, -v226
	v_fma_f32 v227, v105, v146, v227
	v_mul_f32_e32 v226, s88, v226
	v_mul_f32_e32 v227, s88, v227
	v_cvt_pk_bf16_f32 v226, v226, v227
	ds_write_b16 v221, v226 offset:2448
	ds_write_b16_d16_hi v221, v226 offset:2512
	s_waitcnt vmcnt(5)
	v_mul_f32_e32 v226, v106, v149
	v_mul_f32_e32 v227, v122, v149
	v_fma_f32 v226, v122, v148, -v226
	v_fma_f32 v227, v106, v148, v227
	v_mul_f32_e32 v226, s88, v226
	v_mul_f32_e32 v227, s88, v227
	v_cvt_pk_bf16_f32 v226, v226, v227
	ds_write_b16 v221, v226 offset:2592
	ds_write_b16_d16_hi v221, v226 offset:2656
	s_waitcnt vmcnt(4)
	v_mul_f32_e32 v226, v107, v151
	v_mul_f32_e32 v227, v123, v151
	v_fma_f32 v226, v123, v150, -v226
	v_fma_f32 v227, v107, v150, v227
	v_mul_f32_e32 v226, s88, v226
	v_mul_f32_e32 v227, s88, v227
	v_cvt_pk_bf16_f32 v226, v226, v227
	ds_write_b16 v221, v226 offset:2736
	ds_write_b16_d16_hi v221, v226 offset:2800
	s_waitcnt vmcnt(3)
	v_mul_f32_e32 v226, v108, v153
	v_mul_f32_e32 v227, v124, v153
	v_fma_f32 v226, v124, v152, -v226
	v_fma_f32 v227, v108, v152, v227
	v_mul_f32_e32 v226, s88, v226
	v_mul_f32_e32 v227, s88, v227
	v_cvt_pk_bf16_f32 v226, v226, v227
	ds_write_b16 v221, v226 offset:3456
	ds_write_b16_d16_hi v221, v226 offset:3520
	s_waitcnt vmcnt(2)
	v_mul_f32_e32 v226, v109, v155
	v_mul_f32_e32 v227, v125, v155
	v_fma_f32 v226, v125, v154, -v226
	v_fma_f32 v227, v109, v154, v227
	v_mul_f32_e32 v226, s88, v226
	v_mul_f32_e32 v227, s88, v227
	v_cvt_pk_bf16_f32 v226, v226, v227
	ds_write_b16 v221, v226 offset:3600
	ds_write_b16_d16_hi v221, v226 offset:3664
	s_waitcnt vmcnt(1)
	v_mul_f32_e32 v226, v110, v157
	v_mul_f32_e32 v227, v126, v157
	v_fma_f32 v226, v126, v156, -v226
	v_fma_f32 v227, v110, v156, v227
	v_mul_f32_e32 v226, s88, v226
	v_mul_f32_e32 v227, s88, v227
	v_cvt_pk_bf16_f32 v226, v226, v227
	ds_write_b16 v221, v226 offset:3744
	ds_write_b16_d16_hi v221, v226 offset:3808
	s_waitcnt vmcnt(0)
	v_mul_f32_e32 v226, v111, v159
	v_mul_f32_e32 v227, v127, v159
	v_fma_f32 v226, v127, v158, -v226
	v_fma_f32 v227, v111, v158, v227
	v_mul_f32_e32 v226, s88, v226
	v_mul_f32_e32 v227, s88, v227
	v_cvt_pk_bf16_f32 v226, v226, v227
	ds_write_b16 v221, v226 offset:3888
	ds_write_b16_d16_hi v221, v226 offset:3952
	s_branch .Lep4_00_st

.Lep4_01_mR:
	s_load_dwordx2 s[98:99], s[0:1], 0x148
	v_add_u32_e32 v226, s94, v223
	v_lshlrev_b32_e32 v226, 8, v226
	v_add_u32_e32 v232, v226, v220
	v_mov_b32_e32 v233, 0
	s_waitcnt lgkmcnt(0)
	v_lshl_add_u64 v[232:233], s[98:99], 0, v[232:233]
	global_load_dwordx2 v[128:129], v[232:233], off
	global_load_dwordx2 v[130:131], v[232:233], off offset:256
	global_load_dwordx2 v[132:133], v[232:233], off offset:512
	global_load_dwordx2 v[134:135], v[232:233], off offset:768
	global_load_dwordx2 v[136:137], v[232:233], off offset:2048
	global_load_dwordx2 v[138:139], v[232:233], off offset:2304
	global_load_dwordx2 v[140:141], v[232:233], off offset:2560
	global_load_dwordx2 v[142:143], v[232:233], off offset:2816
	v_add_co_u32_e32 v234, vcc, 0x1000, v232
	s_nop 1
	v_addc_co_u32_e32 v235, vcc, 0, v233, vcc
	global_load_dwordx2 v[144:145], v[234:235], off
	global_load_dwordx2 v[146:147], v[234:235], off offset:256
	global_load_dwordx2 v[148:149], v[234:235], off offset:512
	global_load_dwordx2 v[150:151], v[234:235], off offset:768
	global_load_dwordx2 v[152:153], v[234:235], off offset:2048
	global_load_dwordx2 v[154:155], v[234:235], off offset:2304
	global_load_dwordx2 v[156:157], v[234:235], off offset:2560
	global_load_dwordx2 v[158:159], v[234:235], off offset:2816
	s_waitcnt vmcnt(15)
	v_mul_f32_e32 v226, v64, v129
	v_mul_f32_e32 v227, v80, v129
	v_fma_f32 v226, v80, v128, -v226
	v_fma_f32 v227, v64, v128, v227
	v_mul_f32_e32 v226, s88, v226
	v_mul_f32_e32 v227, s88, v227
	v_cvt_pk_bf16_f32 v226, v226, v227
	ds_write_b16 v221, v226
	ds_write_b16_d16_hi v221, v226 offset:64
	s_waitcnt vmcnt(14)
	v_mul_f32_e32 v226, v65, v131
	v_mul_f32_e32 v227, v81, v131
	v_fma_f32 v226, v81, v130, -v226
	v_fma_f32 v227, v65, v130, v227
	v_mul_f32_e32 v226, s88, v226
	v_mul_f32_e32 v227, s88, v227
	v_cvt_pk_bf16_f32 v226, v226, v227
	ds_write_b16 v221, v226 offset:144
	ds_write_b16_d16_hi v221, v226 offset:208
	s_waitcnt vmcnt(13)
	v_mul_f32_e32 v226, v66, v133
	v_mul_f32_e32 v227, v82, v133
	v_fma_f32 v226, v82, v132, -v226
	v_fma_f32 v227, v66, v132, v227
	v_mul_f32_e32 v226, s88, v226
	v_mul_f32_e32 v227, s88, v227
	v_cvt_pk_bf16_f32 v226, v226, v227
	ds_write_b16 v221, v226 offset:288
	ds_write_b16_d16_hi v221, v226 offset:352
	s_waitcnt vmcnt(12)
	v_mul_f32_e32 v226, v67, v135
	v_mul_f32_e32 v227, v83, v135
	v_fma_f32 v226, v83, v134, -v226
	v_fma_f32 v227, v67, v134, v227
	v_mul_f32_e32 v226, s88, v226
	v_mul_f32_e32 v227, s88, v227
	v_cvt_pk_bf16_f32 v226, v226, v227
	ds_write_b16 v221, v226 offset:432
	ds_write_b16_d16_hi v221, v226 offset:496
	s_waitcnt vmcnt(11)
	v_mul_f32_e32 v226, v68, v137
	v_mul_f32_e32 v227, v84, v137
	v_fma_f32 v226, v84, v136, -v226
	v_fma_f32 v227, v68, v136, v227
	v_mul_f32_e32 v226, s88, v226
	v_mul_f32_e32 v227, s88, v227
	v_cvt_pk_bf16_f32 v226, v226, v227
	ds_write_b16 v221, v226 offset:1152
	ds_write_b16_d16_hi v221, v226 offset:1216
	s_waitcnt vmcnt(10)
	v_mul_f32_e32 v226, v69, v139
	v_mul_f32_e32 v227, v85, v139
	v_fma_f32 v226, v85, v138, -v226
	v_fma_f32 v227, v69, v138, v227
	v_mul_f32_e32 v226, s88, v226
	v_mul_f32_e32 v227, s88, v227
	v_cvt_pk_bf16_f32 v226, v226, v227
	ds_write_b16 v221, v226 offset:1296
	ds_write_b16_d16_hi v221, v226 offset:1360
	s_waitcnt vmcnt(9)
	v_mul_f32_e32 v226, v70, v141
	v_mul_f32_e32 v227, v86, v141
	v_fma_f32 v226, v86, v140, -v226
	v_fma_f32 v227, v70, v140, v227
	v_mul_f32_e32 v226, s88, v226
	v_mul_f32_e32 v227, s88, v227
	v_cvt_pk_bf16_f32 v226, v226, v227
	ds_write_b16 v221, v226 offset:1440
	ds_write_b16_d16_hi v221, v226 offset:1504
	s_waitcnt vmcnt(8)
	v_mul_f32_e32 v226, v71, v143
	v_mul_f32_e32 v227, v87, v143
	v_fma_f32 v226, v87, v142, -v226
	v_fma_f32 v227, v71, v142, v227
	v_mul_f32_e32 v226, s88, v226
	v_mul_f32_e32 v227, s88, v227
	v_cvt_pk_bf16_f32 v226, v226, v227
	ds_write_b16 v221, v226 offset:1584
	ds_write_b16_d16_hi v221, v226 offset:1648
	s_waitcnt vmcnt(7)
	v_mul_f32_e32 v226, v72, v145
	v_mul_f32_e32 v227, v88, v145
	v_fma_f32 v226, v88, v144, -v226
	v_fma_f32 v227, v72, v144, v227
	v_mul_f32_e32 v226, s88, v226
	v_mul_f32_e32 v227, s88, v227
	v_cvt_pk_bf16_f32 v226, v226, v227
	ds_write_b16 v221, v226 offset:2304
	ds_write_b16_d16_hi v221, v226 offset:2368
	s_waitcnt vmcnt(6)
	v_mul_f32_e32 v226, v73, v147
	v_mul_f32_e32 v227, v89, v147
	v_fma_f32 v226, v89, v146, -v226
	v_fma_f32 v227, v73, v146, v227
	v_mul_f32_e32 v226, s88, v226
	v_mul_f32_e32 v227, s88, v227
	v_cvt_pk_bf16_f32 v226, v226, v227
	ds_write_b16 v221, v226 offset:2448
	ds_write_b16_d16_hi v221, v226 offset:2512
	s_waitcnt vmcnt(5)
	v_mul_f32_e32 v226, v74, v149
	v_mul_f32_e32 v227, v90, v149
	v_fma_f32 v226, v90, v148, -v226
	v_fma_f32 v227, v74, v148, v227
	v_mul_f32_e32 v226, s88, v226
	v_mul_f32_e32 v227, s88, v227
	v_cvt_pk_bf16_f32 v226, v226, v227
	ds_write_b16 v221, v226 offset:2592
	ds_write_b16_d16_hi v221, v226 offset:2656
	s_waitcnt vmcnt(4)
	v_mul_f32_e32 v226, v75, v151
	v_mul_f32_e32 v227, v91, v151
	v_fma_f32 v226, v91, v150, -v226
	v_fma_f32 v227, v75, v150, v227
	v_mul_f32_e32 v226, s88, v226
	v_mul_f32_e32 v227, s88, v227
	v_cvt_pk_bf16_f32 v226, v226, v227
	ds_write_b16 v221, v226 offset:2736
	ds_write_b16_d16_hi v221, v226 offset:2800
	s_waitcnt vmcnt(3)
	v_mul_f32_e32 v226, v76, v153
	v_mul_f32_e32 v227, v92, v153
	v_fma_f32 v226, v92, v152, -v226
	v_fma_f32 v227, v76, v152, v227
	v_mul_f32_e32 v226, s88, v226
	v_mul_f32_e32 v227, s88, v227
	v_cvt_pk_bf16_f32 v226, v226, v227
	ds_write_b16 v221, v226 offset:3456
	ds_write_b16_d16_hi v221, v226 offset:3520
	s_waitcnt vmcnt(2)
	v_mul_f32_e32 v226, v77, v155
	v_mul_f32_e32 v227, v93, v155
	v_fma_f32 v226, v93, v154, -v226
	v_fma_f32 v227, v77, v154, v227
	v_mul_f32_e32 v226, s88, v226
	v_mul_f32_e32 v227, s88, v227
	v_cvt_pk_bf16_f32 v226, v226, v227
	ds_write_b16 v221, v226 offset:3600
	ds_write_b16_d16_hi v221, v226 offset:3664
	s_waitcnt vmcnt(1)
	v_mul_f32_e32 v226, v78, v157
	v_mul_f32_e32 v227, v94, v157
	v_fma_f32 v226, v94, v156, -v226
	v_fma_f32 v227, v78, v156, v227
	v_mul_f32_e32 v226, s88, v226
	v_mul_f32_e32 v227, s88, v227
	v_cvt_pk_bf16_f32 v226, v226, v227
	ds_write_b16 v221, v226 offset:3744
	ds_write_b16_d16_hi v221, v226 offset:3808
	s_waitcnt vmcnt(0)
	v_mul_f32_e32 v226, v79, v159
	v_mul_f32_e32 v227, v95, v159
	v_fma_f32 v226, v95, v158, -v226
	v_fma_f32 v227, v79, v158, v227
	v_mul_f32_e32 v226, s88, v226
	v_mul_f32_e32 v227, s88, v227
	v_cvt_pk_bf16_f32 v226, v226, v227
	ds_write_b16 v221, v226 offset:3888
	ds_write_b16_d16_hi v221, v226 offset:3952
	s_branch .Lep4_01_st

.Lep4_10_mR:
	s_load_dwordx2 s[98:99], s[0:1], 0x148
	v_add_u32_e32 v226, s94, v223
	v_lshlrev_b32_e32 v226, 8, v226
	v_add_u32_e32 v232, v226, v220
	v_mov_b32_e32 v233, 0
	s_waitcnt lgkmcnt(0)
	v_lshl_add_u64 v[232:233], s[98:99], 0, v[232:233]
	global_load_dwordx2 v[128:129], v[232:233], off
	global_load_dwordx2 v[130:131], v[232:233], off offset:256
	global_load_dwordx2 v[132:133], v[232:233], off offset:512
	global_load_dwordx2 v[134:135], v[232:233], off offset:768
	global_load_dwordx2 v[136:137], v[232:233], off offset:2048
	global_load_dwordx2 v[138:139], v[232:233], off offset:2304
	global_load_dwordx2 v[140:141], v[232:233], off offset:2560
	global_load_dwordx2 v[142:143], v[232:233], off offset:2816
	v_add_co_u32_e32 v234, vcc, 0x1000, v232
	s_nop 1
	v_addc_co_u32_e32 v235, vcc, 0, v233, vcc
	global_load_dwordx2 v[144:145], v[234:235], off
	global_load_dwordx2 v[146:147], v[234:235], off offset:256
	global_load_dwordx2 v[148:149], v[234:235], off offset:512
	global_load_dwordx2 v[150:151], v[234:235], off offset:768
	global_load_dwordx2 v[152:153], v[234:235], off offset:2048
	global_load_dwordx2 v[154:155], v[234:235], off offset:2304
	global_load_dwordx2 v[156:157], v[234:235], off offset:2560
	global_load_dwordx2 v[158:159], v[234:235], off offset:2816
	s_waitcnt vmcnt(15)
	v_mul_f32_e32 v226, v32, v129
	v_mul_f32_e32 v227, v48, v129
	v_fma_f32 v226, v48, v128, -v226
	v_fma_f32 v227, v32, v128, v227
	v_mul_f32_e32 v226, s88, v226
	v_mul_f32_e32 v227, s88, v227
	v_cvt_pk_bf16_f32 v226, v226, v227
	ds_write_b16 v221, v226
	ds_write_b16_d16_hi v221, v226 offset:64
	s_waitcnt vmcnt(14)
	v_mul_f32_e32 v226, v33, v131
	v_mul_f32_e32 v227, v49, v131
	v_fma_f32 v226, v49, v130, -v226
	v_fma_f32 v227, v33, v130, v227
	v_mul_f32_e32 v226, s88, v226
	v_mul_f32_e32 v227, s88, v227
	v_cvt_pk_bf16_f32 v226, v226, v227
	ds_write_b16 v221, v226 offset:144
	ds_write_b16_d16_hi v221, v226 offset:208
	s_waitcnt vmcnt(13)
	v_mul_f32_e32 v226, v34, v133
	v_mul_f32_e32 v227, v50, v133
	v_fma_f32 v226, v50, v132, -v226
	v_fma_f32 v227, v34, v132, v227
	v_mul_f32_e32 v226, s88, v226
	v_mul_f32_e32 v227, s88, v227
	v_cvt_pk_bf16_f32 v226, v226, v227
	ds_write_b16 v221, v226 offset:288
	ds_write_b16_d16_hi v221, v226 offset:352
	s_waitcnt vmcnt(12)
	v_mul_f32_e32 v226, v35, v135
	v_mul_f32_e32 v227, v51, v135
	v_fma_f32 v226, v51, v134, -v226
	v_fma_f32 v227, v35, v134, v227
	v_mul_f32_e32 v226, s88, v226
	v_mul_f32_e32 v227, s88, v227
	v_cvt_pk_bf16_f32 v226, v226, v227
	ds_write_b16 v221, v226 offset:432
	ds_write_b16_d16_hi v221, v226 offset:496
	s_waitcnt vmcnt(11)
	v_mul_f32_e32 v226, v36, v137
	v_mul_f32_e32 v227, v52, v137
	v_fma_f32 v226, v52, v136, -v226
	v_fma_f32 v227, v36, v136, v227
	v_mul_f32_e32 v226, s88, v226
	v_mul_f32_e32 v227, s88, v227
	v_cvt_pk_bf16_f32 v226, v226, v227
	ds_write_b16 v221, v226 offset:1152
	ds_write_b16_d16_hi v221, v226 offset:1216
	s_waitcnt vmcnt(10)
	v_mul_f32_e32 v226, v37, v139
	v_mul_f32_e32 v227, v53, v139
	v_fma_f32 v226, v53, v138, -v226
	v_fma_f32 v227, v37, v138, v227
	v_mul_f32_e32 v226, s88, v226
	v_mul_f32_e32 v227, s88, v227
	v_cvt_pk_bf16_f32 v226, v226, v227
	ds_write_b16 v221, v226 offset:1296
	ds_write_b16_d16_hi v221, v226 offset:1360
	s_waitcnt vmcnt(9)
	v_mul_f32_e32 v226, v38, v141
	v_mul_f32_e32 v227, v54, v141
	v_fma_f32 v226, v54, v140, -v226
	v_fma_f32 v227, v38, v140, v227
	v_mul_f32_e32 v226, s88, v226
	v_mul_f32_e32 v227, s88, v227
	v_cvt_pk_bf16_f32 v226, v226, v227
	ds_write_b16 v221, v226 offset:1440
	ds_write_b16_d16_hi v221, v226 offset:1504
	s_waitcnt vmcnt(8)
	v_mul_f32_e32 v226, v39, v143
	v_mul_f32_e32 v227, v55, v143
	v_fma_f32 v226, v55, v142, -v226
	v_fma_f32 v227, v39, v142, v227
	v_mul_f32_e32 v226, s88, v226
	v_mul_f32_e32 v227, s88, v227
	v_cvt_pk_bf16_f32 v226, v226, v227
	ds_write_b16 v221, v226 offset:1584
	ds_write_b16_d16_hi v221, v226 offset:1648
	s_waitcnt vmcnt(7)
	v_mul_f32_e32 v226, v40, v145
	v_mul_f32_e32 v227, v56, v145
	v_fma_f32 v226, v56, v144, -v226
	v_fma_f32 v227, v40, v144, v227
	v_mul_f32_e32 v226, s88, v226
	v_mul_f32_e32 v227, s88, v227
	v_cvt_pk_bf16_f32 v226, v226, v227
	ds_write_b16 v221, v226 offset:2304
	ds_write_b16_d16_hi v221, v226 offset:2368
	s_waitcnt vmcnt(6)
	v_mul_f32_e32 v226, v41, v147
	v_mul_f32_e32 v227, v57, v147
	v_fma_f32 v226, v57, v146, -v226
	v_fma_f32 v227, v41, v146, v227
	v_mul_f32_e32 v226, s88, v226
	v_mul_f32_e32 v227, s88, v227
	v_cvt_pk_bf16_f32 v226, v226, v227
	ds_write_b16 v221, v226 offset:2448
	ds_write_b16_d16_hi v221, v226 offset:2512
	s_waitcnt vmcnt(5)
	v_mul_f32_e32 v226, v42, v149
	v_mul_f32_e32 v227, v58, v149
	v_fma_f32 v226, v58, v148, -v226
	v_fma_f32 v227, v42, v148, v227
	v_mul_f32_e32 v226, s88, v226
	v_mul_f32_e32 v227, s88, v227
	v_cvt_pk_bf16_f32 v226, v226, v227
	ds_write_b16 v221, v226 offset:2592
	ds_write_b16_d16_hi v221, v226 offset:2656
	s_waitcnt vmcnt(4)
	v_mul_f32_e32 v226, v43, v151
	v_mul_f32_e32 v227, v59, v151
	v_fma_f32 v226, v59, v150, -v226
	v_fma_f32 v227, v43, v150, v227
	v_mul_f32_e32 v226, s88, v226
	v_mul_f32_e32 v227, s88, v227
	v_cvt_pk_bf16_f32 v226, v226, v227
	ds_write_b16 v221, v226 offset:2736
	ds_write_b16_d16_hi v221, v226 offset:2800
	s_waitcnt vmcnt(3)
	v_mul_f32_e32 v226, v44, v153
	v_mul_f32_e32 v227, v60, v153
	v_fma_f32 v226, v60, v152, -v226
	v_fma_f32 v227, v44, v152, v227
	v_mul_f32_e32 v226, s88, v226
	v_mul_f32_e32 v227, s88, v227
	v_cvt_pk_bf16_f32 v226, v226, v227
	ds_write_b16 v221, v226 offset:3456
	ds_write_b16_d16_hi v221, v226 offset:3520
	s_waitcnt vmcnt(2)
	v_mul_f32_e32 v226, v45, v155
	v_mul_f32_e32 v227, v61, v155
	v_fma_f32 v226, v61, v154, -v226
	v_fma_f32 v227, v45, v154, v227
	v_mul_f32_e32 v226, s88, v226
	v_mul_f32_e32 v227, s88, v227
	v_cvt_pk_bf16_f32 v226, v226, v227
	ds_write_b16 v221, v226 offset:3600
	ds_write_b16_d16_hi v221, v226 offset:3664
	s_waitcnt vmcnt(1)
	v_mul_f32_e32 v226, v46, v157
	v_mul_f32_e32 v227, v62, v157
	v_fma_f32 v226, v62, v156, -v226
	v_fma_f32 v227, v46, v156, v227
	v_mul_f32_e32 v226, s88, v226
	v_mul_f32_e32 v227, s88, v227
	v_cvt_pk_bf16_f32 v226, v226, v227
	ds_write_b16 v221, v226 offset:3744
	ds_write_b16_d16_hi v221, v226 offset:3808
	s_waitcnt vmcnt(0)
	v_mul_f32_e32 v226, v47, v159
	v_mul_f32_e32 v227, v63, v159
	v_fma_f32 v226, v63, v158, -v226
	v_fma_f32 v227, v47, v158, v227
	v_mul_f32_e32 v226, s88, v226
	v_mul_f32_e32 v227, s88, v227
	v_cvt_pk_bf16_f32 v226, v226, v227
	ds_write_b16 v221, v226 offset:3888
	ds_write_b16_d16_hi v221, v226 offset:3952
	s_branch .Lep4_10_st

.Lep4_11_mR:
	s_load_dwordx2 s[98:99], s[0:1], 0x148
	v_add_u32_e32 v226, s94, v223
	v_lshlrev_b32_e32 v226, 8, v226
	v_add_u32_e32 v232, v226, v220
	v_mov_b32_e32 v233, 0
	s_waitcnt lgkmcnt(0)
	v_lshl_add_u64 v[232:233], s[98:99], 0, v[232:233]
	global_load_dwordx2 v[128:129], v[232:233], off
	global_load_dwordx2 v[130:131], v[232:233], off offset:256
	global_load_dwordx2 v[132:133], v[232:233], off offset:512
	global_load_dwordx2 v[134:135], v[232:233], off offset:768
	global_load_dwordx2 v[136:137], v[232:233], off offset:2048
	global_load_dwordx2 v[138:139], v[232:233], off offset:2304
	global_load_dwordx2 v[140:141], v[232:233], off offset:2560
	global_load_dwordx2 v[142:143], v[232:233], off offset:2816
	v_add_co_u32_e32 v234, vcc, 0x1000, v232
	s_nop 1
	v_addc_co_u32_e32 v235, vcc, 0, v233, vcc
	global_load_dwordx2 v[144:145], v[234:235], off
	global_load_dwordx2 v[146:147], v[234:235], off offset:256
	global_load_dwordx2 v[148:149], v[234:235], off offset:512
	global_load_dwordx2 v[150:151], v[234:235], off offset:768
	global_load_dwordx2 v[152:153], v[234:235], off offset:2048
	global_load_dwordx2 v[154:155], v[234:235], off offset:2304
	global_load_dwordx2 v[156:157], v[234:235], off offset:2560
	global_load_dwordx2 v[158:159], v[234:235], off offset:2816
	s_waitcnt vmcnt(15)
	v_mul_f32_e32 v226, v0, v129
	v_mul_f32_e32 v227, v16, v129
	v_fma_f32 v226, v16, v128, -v226
	v_fma_f32 v227, v0, v128, v227
	v_mul_f32_e32 v226, s88, v226
	v_mul_f32_e32 v227, s88, v227
	v_cvt_pk_bf16_f32 v226, v226, v227
	ds_write_b16 v221, v226
	ds_write_b16_d16_hi v221, v226 offset:64
	s_waitcnt vmcnt(14)
	v_mul_f32_e32 v226, v1, v131
	v_mul_f32_e32 v227, v17, v131
	v_fma_f32 v226, v17, v130, -v226
	v_fma_f32 v227, v1, v130, v227
	v_mul_f32_e32 v226, s88, v226
	v_mul_f32_e32 v227, s88, v227
	v_cvt_pk_bf16_f32 v226, v226, v227
	ds_write_b16 v221, v226 offset:144
	ds_write_b16_d16_hi v221, v226 offset:208
	s_waitcnt vmcnt(13)
	v_mul_f32_e32 v226, v2, v133
	v_mul_f32_e32 v227, v18, v133
	v_fma_f32 v226, v18, v132, -v226
	v_fma_f32 v227, v2, v132, v227
	v_mul_f32_e32 v226, s88, v226
	v_mul_f32_e32 v227, s88, v227
	v_cvt_pk_bf16_f32 v226, v226, v227
	ds_write_b16 v221, v226 offset:288
	ds_write_b16_d16_hi v221, v226 offset:352
	s_waitcnt vmcnt(12)
	v_mul_f32_e32 v226, v3, v135
	v_mul_f32_e32 v227, v19, v135
	v_fma_f32 v226, v19, v134, -v226
	v_fma_f32 v227, v3, v134, v227
	v_mul_f32_e32 v226, s88, v226
	v_mul_f32_e32 v227, s88, v227
	v_cvt_pk_bf16_f32 v226, v226, v227
	ds_write_b16 v221, v226 offset:432
	ds_write_b16_d16_hi v221, v226 offset:496
	s_waitcnt vmcnt(11)
	v_mul_f32_e32 v226, v4, v137
	v_mul_f32_e32 v227, v20, v137
	v_fma_f32 v226, v20, v136, -v226
	v_fma_f32 v227, v4, v136, v227
	v_mul_f32_e32 v226, s88, v226
	v_mul_f32_e32 v227, s88, v227
	v_cvt_pk_bf16_f32 v226, v226, v227
	ds_write_b16 v221, v226 offset:1152
	ds_write_b16_d16_hi v221, v226 offset:1216
	s_waitcnt vmcnt(10)
	v_mul_f32_e32 v226, v5, v139
	v_mul_f32_e32 v227, v21, v139
	v_fma_f32 v226, v21, v138, -v226
	v_fma_f32 v227, v5, v138, v227
	v_mul_f32_e32 v226, s88, v226
	v_mul_f32_e32 v227, s88, v227
	v_cvt_pk_bf16_f32 v226, v226, v227
	ds_write_b16 v221, v226 offset:1296
	ds_write_b16_d16_hi v221, v226 offset:1360
	s_waitcnt vmcnt(9)
	v_mul_f32_e32 v226, v6, v141
	v_mul_f32_e32 v227, v22, v141
	v_fma_f32 v226, v22, v140, -v226
	v_fma_f32 v227, v6, v140, v227
	v_mul_f32_e32 v226, s88, v226
	v_mul_f32_e32 v227, s88, v227
	v_cvt_pk_bf16_f32 v226, v226, v227
	ds_write_b16 v221, v226 offset:1440
	ds_write_b16_d16_hi v221, v226 offset:1504
	s_waitcnt vmcnt(8)
	v_mul_f32_e32 v226, v7, v143
	v_mul_f32_e32 v227, v23, v143
	v_fma_f32 v226, v23, v142, -v226
	v_fma_f32 v227, v7, v142, v227
	v_mul_f32_e32 v226, s88, v226
	v_mul_f32_e32 v227, s88, v227
	v_cvt_pk_bf16_f32 v226, v226, v227
	ds_write_b16 v221, v226 offset:1584
	ds_write_b16_d16_hi v221, v226 offset:1648
	s_waitcnt vmcnt(7)
	v_mul_f32_e32 v226, v8, v145
	v_mul_f32_e32 v227, v24, v145
	v_fma_f32 v226, v24, v144, -v226
	v_fma_f32 v227, v8, v144, v227
	v_mul_f32_e32 v226, s88, v226
	v_mul_f32_e32 v227, s88, v227
	v_cvt_pk_bf16_f32 v226, v226, v227
	ds_write_b16 v221, v226 offset:2304
	ds_write_b16_d16_hi v221, v226 offset:2368
	s_waitcnt vmcnt(6)
	v_mul_f32_e32 v226, v9, v147
	v_mul_f32_e32 v227, v25, v147
	v_fma_f32 v226, v25, v146, -v226
	v_fma_f32 v227, v9, v146, v227
	v_mul_f32_e32 v226, s88, v226
	v_mul_f32_e32 v227, s88, v227
	v_cvt_pk_bf16_f32 v226, v226, v227
	ds_write_b16 v221, v226 offset:2448
	ds_write_b16_d16_hi v221, v226 offset:2512
	s_waitcnt vmcnt(5)
	v_mul_f32_e32 v226, v10, v149
	v_mul_f32_e32 v227, v26, v149
	v_fma_f32 v226, v26, v148, -v226
	v_fma_f32 v227, v10, v148, v227
	v_mul_f32_e32 v226, s88, v226
	v_mul_f32_e32 v227, s88, v227
	v_cvt_pk_bf16_f32 v226, v226, v227
	ds_write_b16 v221, v226 offset:2592
	ds_write_b16_d16_hi v221, v226 offset:2656
	s_waitcnt vmcnt(4)
	v_mul_f32_e32 v226, v11, v151
	v_mul_f32_e32 v227, v27, v151
	v_fma_f32 v226, v27, v150, -v226
	v_fma_f32 v227, v11, v150, v227
	v_mul_f32_e32 v226, s88, v226
	v_mul_f32_e32 v227, s88, v227
	v_cvt_pk_bf16_f32 v226, v226, v227
	ds_write_b16 v221, v226 offset:2736
	ds_write_b16_d16_hi v221, v226 offset:2800
	s_waitcnt vmcnt(3)
	v_mul_f32_e32 v226, v12, v153
	v_mul_f32_e32 v227, v28, v153
	v_fma_f32 v226, v28, v152, -v226
	v_fma_f32 v227, v12, v152, v227
	v_mul_f32_e32 v226, s88, v226
	v_mul_f32_e32 v227, s88, v227
	v_cvt_pk_bf16_f32 v226, v226, v227
	ds_write_b16 v221, v226 offset:3456
	ds_write_b16_d16_hi v221, v226 offset:3520
	s_waitcnt vmcnt(2)
	v_mul_f32_e32 v226, v13, v155
	v_mul_f32_e32 v227, v29, v155
	v_fma_f32 v226, v29, v154, -v226
	v_fma_f32 v227, v13, v154, v227
	v_mul_f32_e32 v226, s88, v226
	v_mul_f32_e32 v227, s88, v227
	v_cvt_pk_bf16_f32 v226, v226, v227
	ds_write_b16 v221, v226 offset:3600
	ds_write_b16_d16_hi v221, v226 offset:3664
	s_waitcnt vmcnt(1)
	v_mul_f32_e32 v226, v14, v157
	v_mul_f32_e32 v227, v30, v157
	v_fma_f32 v226, v30, v156, -v226
	v_fma_f32 v227, v14, v156, v227
	v_mul_f32_e32 v226, s88, v226
	v_mul_f32_e32 v227, s88, v227
	v_cvt_pk_bf16_f32 v226, v226, v227
	ds_write_b16 v221, v226 offset:3744
	ds_write_b16_d16_hi v221, v226 offset:3808
	s_waitcnt vmcnt(0)
	v_mul_f32_e32 v226, v15, v159
	v_mul_f32_e32 v227, v31, v159
	v_fma_f32 v226, v31, v158, -v226
	v_fma_f32 v227, v15, v158, v227
	v_mul_f32_e32 v226, s88, v226
	v_mul_f32_e32 v227, s88, v227
	v_cvt_pk_bf16_f32 v226, v226, v227
	ds_write_b16 v221, v226 offset:3888
	ds_write_b16_d16_hi v221, v226 offset:3952
	s_branch .Lep4_11_st

.Lep6_11_end:
	s_branch .LBB0_4667
.LBB0_5176:
	s_cmp_lt_i32 s45, 20
	s_cbranch_scc1 .LBB0_5230
	s_waitcnt vmcnt(0)
	v_cmp_eq_u32_e32 vcc, 0, v188
	s_waitcnt lgkmcnt(0)
	s_and_b64 s[4:5], s[46:47], vcc
	s_waitcnt vmcnt(63) expcnt(7) lgkmcnt(15)
	s_barrier
	s_and_saveexec_b64 s[2:3], s[4:5]
	s_cbranch_execz .LBB0_5229
	v_mov_b32_e32 v0, 0x24400
	s_waitcnt vmcnt(0) expcnt(0) lgkmcnt(0)
	ds_read_b32 v2, v0
	v_mov_b32_e32 v0, 0x24404
	ds_read_b32 v0, v0
	s_waitcnt lgkmcnt(1)
	v_cmp_ne_u32_e32 vcc, 0, v2
	s_cbranch_vccnz .LBB0_5193
	s_add_u32 s4, s40, 0x1000
	s_addc_u32 s5, s41, 0
	s_add_u32 s6, s40, 0x1100
	s_addc_u32 s7, s41, 0
	s_add_u32 s8, s40, 0x1200
	s_addc_u32 s9, s41, 0
	s_mul_i32 s18, s43, s33
	s_add_u32 s10, s40, 0x1300
	s_mul_i32 s18, s18, s42
	s_addc_u32 s11, s41, 0
	s_mov_b32 s19, 1
	v_mov_b32_e32 v16, 0
	s_branch .LBB0_5181
